# nt cache hints on once-read streams: P0b x, P2 biasup weights, P4 slots, P6 x (+3/4 out stores), P7 act/edge stores, P9 x1 loads
# speedup vs baseline: 1.0415x; 1.0051x over previous
.Lbu_outer:
	v_lshl_add_u64 v[18:19], s[78:79], 0, v[10:11]
	v_add_co_u32_e32 v18, vcc, 0x7000000, v18
	s_mov_b32 s12, s0
	s_nop 0
	v_addc_co_u32_e32 v19, vcc, 0, v19, vcc
	global_load_dwordx4 v[128:131], v[18:19], off nt
	global_load_dwordx4 v[132:135], v[18:19], off offset:1024 nt
	global_load_dwordx4 v[136:139], v[18:19], off offset:2048 nt
	global_load_dwordx4 v[140:143], v[18:19], off offset:3072 nt
	s_add_i32 s12, s12, s8
	s_cmp_gt_i32 s12, 0x2bff
	s_cselect_b32 s98, 0, s6
	s_cselect_b32 s99, 0, s7
	v_lshl_add_u64 v[26:27], v[18:19], 0, s[98:99]
	global_load_dwordx4 v[144:147], v[26:27], off nt
	global_load_dwordx4 v[148:151], v[26:27], off offset:1024 nt
	global_load_dwordx4 v[152:155], v[26:27], off offset:2048 nt
	global_load_dwordx4 v[156:159], v[26:27], off offset:3072 nt
	s_add_i32 s12, s12, s8
	s_cmp_gt_i32 s12, 0x2bff
	s_cselect_b32 s98, 0, s6
	s_cselect_b32 s99, 0, s7
	v_lshl_add_u64 v[28:29], v[26:27], 0, s[98:99]
	global_load_dwordx4 v[160:163], v[28:29], off nt
	global_load_dwordx4 v[164:167], v[28:29], off offset:1024 nt
	global_load_dwordx4 v[168:171], v[28:29], off offset:2048 nt
	global_load_dwordx4 v[172:175], v[28:29], off offset:3072 nt
	s_add_i32 s12, s12, s8
	s_cmp_gt_i32 s12, 0x2bff
	s_cselect_b32 s98, 0, s6
	s_cselect_b32 s99, 0, s7
	v_lshl_add_u64 v[30:31], v[28:29], 0, s[98:99]
	global_load_dwordx4 v[176:179], v[30:31], off nt
	global_load_dwordx4 v[180:183], v[30:31], off offset:1024 nt
	global_load_dwordx4 v[184:187], v[30:31], off offset:2048 nt
	global_load_dwordx4 v[188:191], v[30:31], off offset:3072 nt
	s_add_i32 s12, s12, s8
	s_cmp_gt_i32 s12, 0x2bff
	s_cselect_b32 s98, 0, s6
	s_cselect_b32 s99, 0, s7
	v_lshl_add_u64 v[32:33], v[30:31], 0, s[98:99]
	global_load_dwordx4 v[64:67], v[32:33], off nt
	global_load_dwordx4 v[68:71], v[32:33], off offset:1024 nt
	global_load_dwordx4 v[72:75], v[32:33], off offset:2048 nt
	global_load_dwordx4 v[76:79], v[32:33], off offset:3072 nt
	s_add_i32 s12, s12, s8
	s_cmp_gt_i32 s12, 0x2bff
	s_cselect_b32 s98, 0, s6
	s_cselect_b32 s99, 0, s7
	v_lshl_add_u64 v[34:35], v[32:33], 0, s[98:99]
	global_load_dwordx4 v[80:83], v[34:35], off nt
	global_load_dwordx4 v[84:87], v[34:35], off offset:1024 nt
	global_load_dwordx4 v[88:91], v[34:35], off offset:2048 nt
	global_load_dwordx4 v[92:95], v[34:35], off offset:3072 nt
	s_waitcnt vmcnt(20)
	v_lshlrev_b32_e32 v36, 16, v128
	v_and_b32_e32 v128, 0xffff0000, v128
	v_lshlrev_b32_e32 v37, 16, v129
	v_and_b32_e32 v129, 0xffff0000, v129
	v_lshlrev_b32_e32 v38, 16, v130
	v_and_b32_e32 v130, 0xffff0000, v130
	v_lshlrev_b32_e32 v39, 16, v131
	v_and_b32_e32 v131, 0xffff0000, v131
	v_mul_f32_e32 v128, v97, v128
	v_mul_f32_e32 v129, v99, v129
	v_mul_f32_e32 v130, v101, v130
	v_mul_f32_e32 v131, v103, v131
	v_fmac_f32_e32 v128, v96, v36
	v_fmac_f32_e32 v129, v98, v37
	v_fmac_f32_e32 v130, v100, v38
	v_fmac_f32_e32 v131, v102, v39
	v_add_f32_e32 v40, v128, v129
	v_add_f32_e32 v40, v130, v40
	v_add_f32_e32 v40, v131, v40
	v_add_f32_e32 v20, 0, v40
	v_lshlrev_b32_e32 v36, 16, v132
	v_and_b32_e32 v132, 0xffff0000, v132
	v_lshlrev_b32_e32 v37, 16, v133
	v_and_b32_e32 v133, 0xffff0000, v133
	v_lshlrev_b32_e32 v38, 16, v134
	v_and_b32_e32 v134, 0xffff0000, v134
	v_lshlrev_b32_e32 v39, 16, v135
	v_and_b32_e32 v135, 0xffff0000, v135
	v_mul_f32_e32 v132, v105, v132
	v_mul_f32_e32 v133, v107, v133
	v_mul_f32_e32 v134, v109, v134
	v_mul_f32_e32 v135, v111, v135
	v_fmac_f32_e32 v132, v104, v36
	v_fmac_f32_e32 v133, v106, v37
	v_fmac_f32_e32 v134, v108, v38
	v_fmac_f32_e32 v135, v110, v39
	v_add_f32_e32 v40, v132, v133
	v_add_f32_e32 v40, v134, v40
	v_add_f32_e32 v40, v135, v40
	v_add_f32_e32 v20, v20, v40
	v_lshlrev_b32_e32 v36, 16, v136
	v_and_b32_e32 v136, 0xffff0000, v136
	v_lshlrev_b32_e32 v37, 16, v137
	v_and_b32_e32 v137, 0xffff0000, v137
	v_lshlrev_b32_e32 v38, 16, v138
	v_and_b32_e32 v138, 0xffff0000, v138
	v_lshlrev_b32_e32 v39, 16, v139
	v_and_b32_e32 v139, 0xffff0000, v139
	v_mul_f32_e32 v136, v113, v136
	v_mul_f32_e32 v137, v115, v137
	v_mul_f32_e32 v138, v117, v138
	v_mul_f32_e32 v139, v119, v139
	v_fmac_f32_e32 v136, v112, v36
	v_fmac_f32_e32 v137, v114, v37
	v_fmac_f32_e32 v138, v116, v38
	v_fmac_f32_e32 v139, v118, v39
	v_add_f32_e32 v40, v136, v137
	v_add_f32_e32 v40, v138, v40
	v_add_f32_e32 v40, v139, v40
	v_add_f32_e32 v20, v20, v40
	v_lshlrev_b32_e32 v36, 16, v140
	v_and_b32_e32 v140, 0xffff0000, v140
	v_lshlrev_b32_e32 v37, 16, v141
	v_and_b32_e32 v141, 0xffff0000, v141
	v_lshlrev_b32_e32 v38, 16, v142
	v_and_b32_e32 v142, 0xffff0000, v142
	v_lshlrev_b32_e32 v39, 16, v143
	v_and_b32_e32 v143, 0xffff0000, v143
	v_mul_f32_e32 v140, v121, v140
	v_mul_f32_e32 v141, v123, v141
	v_mul_f32_e32 v142, v125, v142
	v_mul_f32_e32 v143, v127, v143
	v_fmac_f32_e32 v140, v120, v36
	v_fmac_f32_e32 v141, v122, v37
	v_fmac_f32_e32 v142, v124, v38
	v_fmac_f32_e32 v143, v126, v39
	v_add_f32_e32 v40, v140, v141
	v_add_f32_e32 v40, v142, v40
	v_add_f32_e32 v40, v143, v40
	v_add_f32_e32 v20, v20, v40
	s_waitcnt vmcnt(16)
	v_lshlrev_b32_e32 v36, 16, v144
	v_and_b32_e32 v144, 0xffff0000, v144
	v_lshlrev_b32_e32 v37, 16, v145
	v_and_b32_e32 v145, 0xffff0000, v145
	v_lshlrev_b32_e32 v38, 16, v146
	v_and_b32_e32 v146, 0xffff0000, v146
	v_lshlrev_b32_e32 v39, 16, v147
	v_and_b32_e32 v147, 0xffff0000, v147
	v_mul_f32_e32 v144, v97, v144
	v_mul_f32_e32 v145, v99, v145
	v_mul_f32_e32 v146, v101, v146
	v_mul_f32_e32 v147, v103, v147
	v_fmac_f32_e32 v144, v96, v36
	v_fmac_f32_e32 v145, v98, v37
	v_fmac_f32_e32 v146, v100, v38
	v_fmac_f32_e32 v147, v102, v39
	v_add_f32_e32 v40, v144, v145
	v_add_f32_e32 v40, v146, v40
	v_add_f32_e32 v40, v147, v40
	v_add_f32_e32 v21, 0, v40
	v_lshlrev_b32_e32 v36, 16, v148
	v_and_b32_e32 v148, 0xffff0000, v148
	v_lshlrev_b32_e32 v37, 16, v149
	v_and_b32_e32 v149, 0xffff0000, v149
	v_lshlrev_b32_e32 v38, 16, v150
	v_and_b32_e32 v150, 0xffff0000, v150
	v_lshlrev_b32_e32 v39, 16, v151
	v_and_b32_e32 v151, 0xffff0000, v151
	v_mul_f32_e32 v148, v105, v148
	v_mul_f32_e32 v149, v107, v149
	v_mul_f32_e32 v150, v109, v150
	v_mul_f32_e32 v151, v111, v151
	v_fmac_f32_e32 v148, v104, v36
	v_fmac_f32_e32 v149, v106, v37
	v_fmac_f32_e32 v150, v108, v38
	v_fmac_f32_e32 v151, v110, v39
	v_add_f32_e32 v40, v148, v149
	v_add_f32_e32 v40, v150, v40
	v_add_f32_e32 v40, v151, v40
	v_add_f32_e32 v21, v21, v40
	v_lshlrev_b32_e32 v36, 16, v152
	v_and_b32_e32 v152, 0xffff0000, v152
	v_lshlrev_b32_e32 v37, 16, v153
	v_and_b32_e32 v153, 0xffff0000, v153
	v_lshlrev_b32_e32 v38, 16, v154
	v_and_b32_e32 v154, 0xffff0000, v154
	v_lshlrev_b32_e32 v39, 16, v155
	v_and_b32_e32 v155, 0xffff0000, v155
	v_mul_f32_e32 v152, v113, v152
	v_mul_f32_e32 v153, v115, v153
	v_mul_f32_e32 v154, v117, v154
	v_mul_f32_e32 v155, v119, v155
	v_fmac_f32_e32 v152, v112, v36
	v_fmac_f32_e32 v153, v114, v37
	v_fmac_f32_e32 v154, v116, v38
	v_fmac_f32_e32 v155, v118, v39
	v_add_f32_e32 v40, v152, v153
	v_add_f32_e32 v40, v154, v40
	v_add_f32_e32 v40, v155, v40
	v_add_f32_e32 v21, v21, v40
	v_lshlrev_b32_e32 v36, 16, v156
	v_and_b32_e32 v156, 0xffff0000, v156
	v_lshlrev_b32_e32 v37, 16, v157
	v_and_b32_e32 v157, 0xffff0000, v157
	v_lshlrev_b32_e32 v38, 16, v158
	v_and_b32_e32 v158, 0xffff0000, v158
	v_lshlrev_b32_e32 v39, 16, v159
	v_and_b32_e32 v159, 0xffff0000, v159
	v_mul_f32_e32 v156, v121, v156
	v_mul_f32_e32 v157, v123, v157
	v_mul_f32_e32 v158, v125, v158
	v_mul_f32_e32 v159, v127, v159
	v_fmac_f32_e32 v156, v120, v36
	v_fmac_f32_e32 v157, v122, v37
	v_fmac_f32_e32 v158, v124, v38
	v_fmac_f32_e32 v159, v126, v39
	v_add_f32_e32 v40, v156, v157
	v_add_f32_e32 v40, v158, v40
	v_add_f32_e32 v40, v159, v40
	v_add_f32_e32 v21, v21, v40
	s_waitcnt vmcnt(12)
	v_lshlrev_b32_e32 v36, 16, v160
	v_and_b32_e32 v160, 0xffff0000, v160
	v_lshlrev_b32_e32 v37, 16, v161
	v_and_b32_e32 v161, 0xffff0000, v161
	v_lshlrev_b32_e32 v38, 16, v162
	v_and_b32_e32 v162, 0xffff0000, v162
	v_lshlrev_b32_e32 v39, 16, v163
	v_and_b32_e32 v163, 0xffff0000, v163
	v_mul_f32_e32 v160, v97, v160
	v_mul_f32_e32 v161, v99, v161
	v_mul_f32_e32 v162, v101, v162
	v_mul_f32_e32 v163, v103, v163
	v_fmac_f32_e32 v160, v96, v36
	v_fmac_f32_e32 v161, v98, v37
	v_fmac_f32_e32 v162, v100, v38
	v_fmac_f32_e32 v163, v102, v39
	v_add_f32_e32 v40, v160, v161
	v_add_f32_e32 v40, v162, v40
	v_add_f32_e32 v40, v163, v40
	v_add_f32_e32 v22, 0, v40
	v_lshlrev_b32_e32 v36, 16, v164
	v_and_b32_e32 v164, 0xffff0000, v164
	v_lshlrev_b32_e32 v37, 16, v165
	v_and_b32_e32 v165, 0xffff0000, v165
	v_lshlrev_b32_e32 v38, 16, v166
	v_and_b32_e32 v166, 0xffff0000, v166
	v_lshlrev_b32_e32 v39, 16, v167
	v_and_b32_e32 v167, 0xffff0000, v167
	v_mul_f32_e32 v164, v105, v164
	v_mul_f32_e32 v165, v107, v165
	v_mul_f32_e32 v166, v109, v166
	v_mul_f32_e32 v167, v111, v167
	v_fmac_f32_e32 v164, v104, v36
	v_fmac_f32_e32 v165, v106, v37
	v_fmac_f32_e32 v166, v108, v38
	v_fmac_f32_e32 v167, v110, v39
	v_add_f32_e32 v40, v164, v165
	v_add_f32_e32 v40, v166, v40
	v_add_f32_e32 v40, v167, v40
	v_add_f32_e32 v22, v22, v40
	v_lshlrev_b32_e32 v36, 16, v168
	v_and_b32_e32 v168, 0xffff0000, v168
	v_lshlrev_b32_e32 v37, 16, v169
	v_and_b32_e32 v169, 0xffff0000, v169
	v_lshlrev_b32_e32 v38, 16, v170
	v_and_b32_e32 v170, 0xffff0000, v170
	v_lshlrev_b32_e32 v39, 16, v171
	v_and_b32_e32 v171, 0xffff0000, v171
	v_mul_f32_e32 v168, v113, v168
	v_mul_f32_e32 v169, v115, v169
	v_mul_f32_e32 v170, v117, v170
	v_mul_f32_e32 v171, v119, v171
	v_fmac_f32_e32 v168, v112, v36
	v_fmac_f32_e32 v169, v114, v37
	v_fmac_f32_e32 v170, v116, v38
	v_fmac_f32_e32 v171, v118, v39
	v_add_f32_e32 v40, v168, v169
	v_add_f32_e32 v40, v170, v40
	v_add_f32_e32 v40, v171, v40
	v_add_f32_e32 v22, v22, v40
	v_lshlrev_b32_e32 v36, 16, v172
	v_and_b32_e32 v172, 0xffff0000, v172
	v_lshlrev_b32_e32 v37, 16, v173
	v_and_b32_e32 v173, 0xffff0000, v173
	v_lshlrev_b32_e32 v38, 16, v174
	v_and_b32_e32 v174, 0xffff0000, v174
	v_lshlrev_b32_e32 v39, 16, v175
	v_and_b32_e32 v175, 0xffff0000, v175
	v_mul_f32_e32 v172, v121, v172
	v_mul_f32_e32 v173, v123, v173
	v_mul_f32_e32 v174, v125, v174
	v_mul_f32_e32 v175, v127, v175
	v_fmac_f32_e32 v172, v120, v36
	v_fmac_f32_e32 v173, v122, v37
	v_fmac_f32_e32 v174, v124, v38
	v_fmac_f32_e32 v175, v126, v39
	v_add_f32_e32 v40, v172, v173
	v_add_f32_e32 v40, v174, v40
	v_add_f32_e32 v40, v175, v40
	v_add_f32_e32 v22, v22, v40
	s_waitcnt vmcnt(8)
	v_lshlrev_b32_e32 v36, 16, v176
	v_and_b32_e32 v176, 0xffff0000, v176
	v_lshlrev_b32_e32 v37, 16, v177
	v_and_b32_e32 v177, 0xffff0000, v177
	v_lshlrev_b32_e32 v38, 16, v178
	v_and_b32_e32 v178, 0xffff0000, v178
	v_lshlrev_b32_e32 v39, 16, v179
	v_and_b32_e32 v179, 0xffff0000, v179
	v_mul_f32_e32 v176, v97, v176
	v_mul_f32_e32 v177, v99, v177
	v_mul_f32_e32 v178, v101, v178
	v_mul_f32_e32 v179, v103, v179
	v_fmac_f32_e32 v176, v96, v36
	v_fmac_f32_e32 v177, v98, v37
	v_fmac_f32_e32 v178, v100, v38
	v_fmac_f32_e32 v179, v102, v39
	v_add_f32_e32 v40, v176, v177
	v_add_f32_e32 v40, v178, v40
	v_add_f32_e32 v40, v179, v40
	v_add_f32_e32 v23, 0, v40
	v_lshlrev_b32_e32 v36, 16, v180
	v_and_b32_e32 v180, 0xffff0000, v180
	v_lshlrev_b32_e32 v37, 16, v181
	v_and_b32_e32 v181, 0xffff0000, v181
	v_lshlrev_b32_e32 v38, 16, v182
	v_and_b32_e32 v182, 0xffff0000, v182
	v_lshlrev_b32_e32 v39, 16, v183
	v_and_b32_e32 v183, 0xffff0000, v183
	v_mul_f32_e32 v180, v105, v180
	v_mul_f32_e32 v181, v107, v181
	v_mul_f32_e32 v182, v109, v182
	v_mul_f32_e32 v183, v111, v183
	v_fmac_f32_e32 v180, v104, v36
	v_fmac_f32_e32 v181, v106, v37
	v_fmac_f32_e32 v182, v108, v38
	v_fmac_f32_e32 v183, v110, v39
	v_add_f32_e32 v40, v180, v181
	v_add_f32_e32 v40, v182, v40
	v_add_f32_e32 v40, v183, v40
	v_add_f32_e32 v23, v23, v40
	v_lshlrev_b32_e32 v36, 16, v184
	v_and_b32_e32 v184, 0xffff0000, v184
	v_lshlrev_b32_e32 v37, 16, v185
	v_and_b32_e32 v185, 0xffff0000, v185
	v_lshlrev_b32_e32 v38, 16, v186
	v_and_b32_e32 v186, 0xffff0000, v186
	v_lshlrev_b32_e32 v39, 16, v187
	v_and_b32_e32 v187, 0xffff0000, v187
	v_mul_f32_e32 v184, v113, v184
	v_mul_f32_e32 v185, v115, v185
	v_mul_f32_e32 v186, v117, v186
	v_mul_f32_e32 v187, v119, v187
	v_fmac_f32_e32 v184, v112, v36
	v_fmac_f32_e32 v185, v114, v37
	v_fmac_f32_e32 v186, v116, v38
	v_fmac_f32_e32 v187, v118, v39
	v_add_f32_e32 v40, v184, v185
	v_add_f32_e32 v40, v186, v40
	v_add_f32_e32 v40, v187, v40
	v_add_f32_e32 v23, v23, v40
	v_lshlrev_b32_e32 v36, 16, v188
	v_and_b32_e32 v188, 0xffff0000, v188
	v_lshlrev_b32_e32 v37, 16, v189
	v_and_b32_e32 v189, 0xffff0000, v189
	v_lshlrev_b32_e32 v38, 16, v190
	v_and_b32_e32 v190, 0xffff0000, v190
	v_lshlrev_b32_e32 v39, 16, v191
	v_and_b32_e32 v191, 0xffff0000, v191
	v_mul_f32_e32 v188, v121, v188
	v_mul_f32_e32 v189, v123, v189
	v_mul_f32_e32 v190, v125, v190
	v_mul_f32_e32 v191, v127, v191
	v_fmac_f32_e32 v188, v120, v36
	v_fmac_f32_e32 v189, v122, v37
	v_fmac_f32_e32 v190, v124, v38
	v_fmac_f32_e32 v191, v126, v39
	v_add_f32_e32 v40, v188, v189
	v_add_f32_e32 v40, v190, v40
	v_add_f32_e32 v40, v191, v40
	v_add_f32_e32 v23, v23, v40
	s_waitcnt vmcnt(4)
	v_lshlrev_b32_e32 v36, 16, v64
	v_and_b32_e32 v64, 0xffff0000, v64
	v_lshlrev_b32_e32 v37, 16, v65
	v_and_b32_e32 v65, 0xffff0000, v65
	v_lshlrev_b32_e32 v38, 16, v66
	v_and_b32_e32 v66, 0xffff0000, v66
	v_lshlrev_b32_e32 v39, 16, v67
	v_and_b32_e32 v67, 0xffff0000, v67
	v_mul_f32_e32 v64, v97, v64
	v_mul_f32_e32 v65, v99, v65
	v_mul_f32_e32 v66, v101, v66
	v_mul_f32_e32 v67, v103, v67
	v_fmac_f32_e32 v64, v96, v36
	v_fmac_f32_e32 v65, v98, v37
	v_fmac_f32_e32 v66, v100, v38
	v_fmac_f32_e32 v67, v102, v39
	v_add_f32_e32 v40, v64, v65
	v_add_f32_e32 v40, v66, v40
	v_add_f32_e32 v40, v67, v40
	v_add_f32_e32 v24, 0, v40
	v_lshlrev_b32_e32 v36, 16, v68
	v_and_b32_e32 v68, 0xffff0000, v68
	v_lshlrev_b32_e32 v37, 16, v69
	v_and_b32_e32 v69, 0xffff0000, v69
	v_lshlrev_b32_e32 v38, 16, v70
	v_and_b32_e32 v70, 0xffff0000, v70
	v_lshlrev_b32_e32 v39, 16, v71
	v_and_b32_e32 v71, 0xffff0000, v71
	v_mul_f32_e32 v68, v105, v68
	v_mul_f32_e32 v69, v107, v69
	v_mul_f32_e32 v70, v109, v70
	v_mul_f32_e32 v71, v111, v71
	v_fmac_f32_e32 v68, v104, v36
	v_fmac_f32_e32 v69, v106, v37
	v_fmac_f32_e32 v70, v108, v38
	v_fmac_f32_e32 v71, v110, v39
	v_add_f32_e32 v40, v68, v69
	v_add_f32_e32 v40, v70, v40
	v_add_f32_e32 v40, v71, v40
	v_add_f32_e32 v24, v24, v40
	v_lshlrev_b32_e32 v36, 16, v72
	v_and_b32_e32 v72, 0xffff0000, v72
	v_lshlrev_b32_e32 v37, 16, v73
	v_and_b32_e32 v73, 0xffff0000, v73
	v_lshlrev_b32_e32 v38, 16, v74
	v_and_b32_e32 v74, 0xffff0000, v74
	v_lshlrev_b32_e32 v39, 16, v75
	v_and_b32_e32 v75, 0xffff0000, v75
	v_mul_f32_e32 v72, v113, v72
	v_mul_f32_e32 v73, v115, v73
	v_mul_f32_e32 v74, v117, v74
	v_mul_f32_e32 v75, v119, v75
	v_fmac_f32_e32 v72, v112, v36
	v_fmac_f32_e32 v73, v114, v37
	v_fmac_f32_e32 v74, v116, v38
	v_fmac_f32_e32 v75, v118, v39
	v_add_f32_e32 v40, v72, v73
	v_add_f32_e32 v40, v74, v40
	v_add_f32_e32 v40, v75, v40
	v_add_f32_e32 v24, v24, v40
	v_lshlrev_b32_e32 v36, 16, v76
	v_and_b32_e32 v76, 0xffff0000, v76
	v_lshlrev_b32_e32 v37, 16, v77
	v_and_b32_e32 v77, 0xffff0000, v77
	v_lshlrev_b32_e32 v38, 16, v78
	v_and_b32_e32 v78, 0xffff0000, v78
	v_lshlrev_b32_e32 v39, 16, v79
	v_and_b32_e32 v79, 0xffff0000, v79
	v_mul_f32_e32 v76, v121, v76
	v_mul_f32_e32 v77, v123, v77
	v_mul_f32_e32 v78, v125, v78
	v_mul_f32_e32 v79, v127, v79
	v_fmac_f32_e32 v76, v120, v36
	v_fmac_f32_e32 v77, v122, v37
	v_fmac_f32_e32 v78, v124, v38
	v_fmac_f32_e32 v79, v126, v39
	v_add_f32_e32 v40, v76, v77
	v_add_f32_e32 v40, v78, v40
	v_add_f32_e32 v40, v79, v40
	v_add_f32_e32 v24, v24, v40
	s_waitcnt vmcnt(0)
	v_lshlrev_b32_e32 v36, 16, v80
	v_and_b32_e32 v80, 0xffff0000, v80
	v_lshlrev_b32_e32 v37, 16, v81
	v_and_b32_e32 v81, 0xffff0000, v81
	v_lshlrev_b32_e32 v38, 16, v82
	v_and_b32_e32 v82, 0xffff0000, v82
	v_lshlrev_b32_e32 v39, 16, v83
	v_and_b32_e32 v83, 0xffff0000, v83
	v_mul_f32_e32 v80, v97, v80
	v_mul_f32_e32 v81, v99, v81
	v_mul_f32_e32 v82, v101, v82
	v_mul_f32_e32 v83, v103, v83
	v_fmac_f32_e32 v80, v96, v36
	v_fmac_f32_e32 v81, v98, v37
	v_fmac_f32_e32 v82, v100, v38
	v_fmac_f32_e32 v83, v102, v39
	v_add_f32_e32 v40, v80, v81
	v_add_f32_e32 v40, v82, v40
	v_add_f32_e32 v40, v83, v40
	v_add_f32_e32 v25, 0, v40
	v_lshlrev_b32_e32 v36, 16, v84
	v_and_b32_e32 v84, 0xffff0000, v84
	v_lshlrev_b32_e32 v37, 16, v85
	v_and_b32_e32 v85, 0xffff0000, v85
	v_lshlrev_b32_e32 v38, 16, v86
	v_and_b32_e32 v86, 0xffff0000, v86
	v_lshlrev_b32_e32 v39, 16, v87
	v_and_b32_e32 v87, 0xffff0000, v87
	v_mul_f32_e32 v84, v105, v84
	v_mul_f32_e32 v85, v107, v85
	v_mul_f32_e32 v86, v109, v86
	v_mul_f32_e32 v87, v111, v87
	v_fmac_f32_e32 v84, v104, v36
	v_fmac_f32_e32 v85, v106, v37
	v_fmac_f32_e32 v86, v108, v38
	v_fmac_f32_e32 v87, v110, v39
	v_add_f32_e32 v40, v84, v85
	v_add_f32_e32 v40, v86, v40
	v_add_f32_e32 v40, v87, v40
	v_add_f32_e32 v25, v25, v40
	v_lshlrev_b32_e32 v36, 16, v88
	v_and_b32_e32 v88, 0xffff0000, v88
	v_lshlrev_b32_e32 v37, 16, v89
	v_and_b32_e32 v89, 0xffff0000, v89
	v_lshlrev_b32_e32 v38, 16, v90
	v_and_b32_e32 v90, 0xffff0000, v90
	v_lshlrev_b32_e32 v39, 16, v91
	v_and_b32_e32 v91, 0xffff0000, v91
	v_mul_f32_e32 v88, v113, v88
	v_mul_f32_e32 v89, v115, v89
	v_mul_f32_e32 v90, v117, v90
	v_mul_f32_e32 v91, v119, v91
	v_fmac_f32_e32 v88, v112, v36
	v_fmac_f32_e32 v89, v114, v37
	v_fmac_f32_e32 v90, v116, v38
	v_fmac_f32_e32 v91, v118, v39
	v_add_f32_e32 v40, v88, v89
	v_add_f32_e32 v40, v90, v40
	v_add_f32_e32 v40, v91, v40
	v_add_f32_e32 v25, v25, v40
	v_lshlrev_b32_e32 v36, 16, v92
	v_and_b32_e32 v92, 0xffff0000, v92
	v_lshlrev_b32_e32 v37, 16, v93
	v_and_b32_e32 v93, 0xffff0000, v93
	v_lshlrev_b32_e32 v38, 16, v94
	v_and_b32_e32 v94, 0xffff0000, v94
	v_lshlrev_b32_e32 v39, 16, v95
	v_and_b32_e32 v95, 0xffff0000, v95
	v_mul_f32_e32 v92, v121, v92
	v_mul_f32_e32 v93, v123, v93
	v_mul_f32_e32 v94, v125, v94
	v_mul_f32_e32 v95, v127, v95
	v_fmac_f32_e32 v92, v120, v36
	v_fmac_f32_e32 v93, v122, v37
	v_fmac_f32_e32 v94, v124, v38
	v_fmac_f32_e32 v95, v126, v39
	v_add_f32_e32 v40, v92, v93
	v_add_f32_e32 v40, v94, v40
	v_add_f32_e32 v40, v95, v40
	v_add_f32_e32 v25, v25, v40
	ds_bpermute_b32 v42, v12, v20
	ds_bpermute_b32 v43, v12, v21
	ds_bpermute_b32 v44, v12, v22
	ds_bpermute_b32 v45, v12, v23
	ds_bpermute_b32 v46, v12, v24
	ds_bpermute_b32 v47, v12, v25
	s_waitcnt lgkmcnt(0)
	v_add_f32_e32 v20, v20, v42
	v_add_f32_e32 v21, v21, v43
	v_add_f32_e32 v22, v22, v44
	v_add_f32_e32 v23, v23, v45
	v_add_f32_e32 v24, v24, v46
	v_add_f32_e32 v25, v25, v47
	ds_bpermute_b32 v42, v13, v20
	ds_bpermute_b32 v43, v13, v21
	ds_bpermute_b32 v44, v13, v22
	ds_bpermute_b32 v45, v13, v23
	ds_bpermute_b32 v46, v13, v24
	ds_bpermute_b32 v47, v13, v25
	s_waitcnt lgkmcnt(0)
	v_add_f32_e32 v20, v20, v42
	v_add_f32_e32 v21, v21, v43
	v_add_f32_e32 v22, v22, v44
	v_add_f32_e32 v23, v23, v45
	v_add_f32_e32 v24, v24, v46
	v_add_f32_e32 v25, v25, v47
	ds_bpermute_b32 v42, v14, v20
	ds_bpermute_b32 v43, v14, v21
	ds_bpermute_b32 v44, v14, v22
	ds_bpermute_b32 v45, v14, v23
	ds_bpermute_b32 v46, v14, v24
	ds_bpermute_b32 v47, v14, v25
	s_waitcnt lgkmcnt(0)
	v_add_f32_e32 v20, v20, v42
	v_add_f32_e32 v21, v21, v43
	v_add_f32_e32 v22, v22, v44
	v_add_f32_e32 v23, v23, v45
	v_add_f32_e32 v24, v24, v46
	v_add_f32_e32 v25, v25, v47
	ds_bpermute_b32 v42, v15, v20
	ds_bpermute_b32 v43, v15, v21
	ds_bpermute_b32 v44, v15, v22
	ds_bpermute_b32 v45, v15, v23
	ds_bpermute_b32 v46, v15, v24
	ds_bpermute_b32 v47, v15, v25
	s_waitcnt lgkmcnt(0)
	v_add_f32_e32 v20, v20, v42
	v_add_f32_e32 v21, v21, v43
	v_add_f32_e32 v22, v22, v44
	v_add_f32_e32 v23, v23, v45
	v_add_f32_e32 v24, v24, v46
	v_add_f32_e32 v25, v25, v47
	ds_bpermute_b32 v42, v16, v20
	ds_bpermute_b32 v43, v16, v21
	ds_bpermute_b32 v44, v16, v22
	ds_bpermute_b32 v45, v16, v23
	ds_bpermute_b32 v46, v16, v24
	ds_bpermute_b32 v47, v16, v25
	s_waitcnt lgkmcnt(0)
	v_add_f32_e32 v20, v20, v42
	v_add_f32_e32 v21, v21, v43
	v_add_f32_e32 v22, v22, v44
	v_add_f32_e32 v23, v23, v45
	v_add_f32_e32 v24, v24, v46
	v_add_f32_e32 v25, v25, v47
	ds_bpermute_b32 v42, v17, v20
	ds_bpermute_b32 v43, v17, v21
	ds_bpermute_b32 v44, v17, v22
	ds_bpermute_b32 v45, v17, v23
	ds_bpermute_b32 v46, v17, v24
	ds_bpermute_b32 v47, v17, v25
	s_waitcnt lgkmcnt(0)
	v_add_f32_e32 v20, v20, v42
	v_add_f32_e32 v21, v21, v43
	v_add_f32_e32 v22, v22, v44
	v_add_f32_e32 v23, v23, v45
	v_add_f32_e32 v24, v24, v46
	v_add_f32_e32 v25, v25, v47
	s_and_saveexec_b64 s[100:101], s[4:5]
	s_add_u32 s12, s78, s10
	s_addc_u32 s13, s79, s11
	s_mov_b32 s98, s0
	global_store_dword v1, v20, s[12:13]
	s_add_i32 s98, s98, s8
	s_cmp_gt_i32 s98, 0x2bff
	s_cbranch_scc1 .Lbu_st_done
	s_add_u32 s12, s12, s2
	s_addc_u32 s13, s13, s3
	global_store_dword v1, v21, s[12:13]
	s_add_i32 s98, s98, s8
	s_cmp_gt_i32 s98, 0x2bff
	s_cbranch_scc1 .Lbu_st_done
	s_add_u32 s12, s12, s2
	s_addc_u32 s13, s13, s3
	global_store_dword v1, v22, s[12:13]
	s_add_i32 s98, s98, s8
	s_cmp_gt_i32 s98, 0x2bff
	s_cbranch_scc1 .Lbu_st_done
	s_add_u32 s12, s12, s2
	s_addc_u32 s13, s13, s3
	global_store_dword v1, v23, s[12:13]
	s_add_i32 s98, s98, s8
	s_cmp_gt_i32 s98, 0x2bff
	s_cbranch_scc1 .Lbu_st_done
	s_add_u32 s12, s12, s2
	s_addc_u32 s13, s13, s3
	global_store_dword v1, v24, s[12:13]
	s_add_i32 s98, s98, s8
	s_cmp_gt_i32 s98, 0x2bff
	s_cbranch_scc1 .Lbu_st_done
	s_add_u32 s12, s12, s2
	s_addc_u32 s13, s13, s3
	global_store_dword v1, v25, s[12:13]

.Lc4_outer:
	v_mov_b32_e32 v52, v20
	s_mov_b32 s12, s11
	v_cmp_gt_i32_e64 s[14:15], s10, v52
	v_mov_b32_e32 v55, 0
	s_nop 0
	v_cndmask_b32_e64 v52, v20, v52, s[14:15]
	v_ashrrev_i32_e32 v54, 7, v52
	v_ashrrev_i32_e32 v56, 15, v52
	v_lshlrev_b64 v[160:161], 13, v[54:55]
	v_lshlrev_b64 v[164:165], 7, v[54:55]
	v_lshl_add_u64 v[160:161], v[2:3], 0, v[160:161]
	v_lshl_add_u64 v[164:165], v[4:5], 0, v[164:165]
	v_lshl_add_u64 v[162:163], v[160:161], 0, s[6:7]
	global_load_dwordx4 v[32:35], v[160:161], off nt
	global_load_dword v48, v[164:165], off
	global_load_dwordx4 v[36:39], v[160:161], off offset:2048 nt
	global_load_dword v49, v[164:165], off offset:32
	global_load_dwordx4 v[40:43], v[162:163], off nt
	global_load_dword v50, v[164:165], off offset:64
	global_load_dwordx4 v[44:47], v[162:163], off offset:2048 nt
	global_load_dword v51, v[164:165], off offset:96
	v_add_u32_e32 v84, s12, v20
	s_add_i32 s12, s12, s11
	v_cmp_gt_i32_e64 s[16:17], s10, v84
	v_mov_b32_e32 v87, 0
	s_nop 0
	v_cndmask_b32_e64 v84, v20, v84, s[16:17]
	v_ashrrev_i32_e32 v86, 7, v84
	v_ashrrev_i32_e32 v88, 15, v84
	v_lshlrev_b64 v[160:161], 13, v[86:87]
	v_lshlrev_b64 v[164:165], 7, v[86:87]
	v_lshl_add_u64 v[160:161], v[2:3], 0, v[160:161]
	v_lshl_add_u64 v[164:165], v[4:5], 0, v[164:165]
	v_lshl_add_u64 v[162:163], v[160:161], 0, s[6:7]
	global_load_dwordx4 v[64:67], v[160:161], off nt
	global_load_dword v80, v[164:165], off
	global_load_dwordx4 v[68:71], v[160:161], off offset:2048 nt
	global_load_dword v81, v[164:165], off offset:32
	global_load_dwordx4 v[72:75], v[162:163], off nt
	global_load_dword v82, v[164:165], off offset:64
	global_load_dwordx4 v[76:79], v[162:163], off offset:2048 nt
	global_load_dword v83, v[164:165], off offset:96
	v_add_u32_e32 v116, s12, v20
	s_add_i32 s12, s12, s11
	v_cmp_gt_i32_e64 s[18:19], s10, v116
	v_mov_b32_e32 v119, 0
	s_nop 0
	v_cndmask_b32_e64 v116, v20, v116, s[18:19]
	v_ashrrev_i32_e32 v118, 7, v116
	v_ashrrev_i32_e32 v120, 15, v116
	v_lshlrev_b64 v[160:161], 13, v[118:119]
	v_lshlrev_b64 v[164:165], 7, v[118:119]
	v_lshl_add_u64 v[160:161], v[2:3], 0, v[160:161]
	v_lshl_add_u64 v[164:165], v[4:5], 0, v[164:165]
	v_lshl_add_u64 v[162:163], v[160:161], 0, s[6:7]
	global_load_dwordx4 v[96:99], v[160:161], off nt
	global_load_dword v112, v[164:165], off
	global_load_dwordx4 v[100:103], v[160:161], off offset:2048 nt
	global_load_dword v113, v[164:165], off offset:32
	global_load_dwordx4 v[104:107], v[162:163], off nt
	global_load_dword v114, v[164:165], off offset:64
	global_load_dwordx4 v[108:111], v[162:163], off offset:2048 nt
	global_load_dword v115, v[164:165], off offset:96
	v_add_u32_e32 v148, s12, v20
	v_cmp_gt_i32_e64 s[20:21], s10, v148
	v_mov_b32_e32 v151, 0
	s_nop 0
	v_cndmask_b32_e64 v148, v20, v148, s[20:21]
	v_ashrrev_i32_e32 v150, 7, v148
	v_ashrrev_i32_e32 v152, 15, v148
	v_lshlrev_b64 v[160:161], 13, v[150:151]
	v_lshlrev_b64 v[164:165], 7, v[150:151]
	v_lshl_add_u64 v[160:161], v[2:3], 0, v[160:161]
	v_lshl_add_u64 v[164:165], v[4:5], 0, v[164:165]
	v_lshl_add_u64 v[162:163], v[160:161], 0, s[6:7]
	global_load_dwordx4 v[128:131], v[160:161], off nt
	global_load_dword v144, v[164:165], off
	global_load_dwordx4 v[132:135], v[160:161], off offset:2048 nt
	global_load_dword v145, v[164:165], off offset:32
	global_load_dwordx4 v[136:139], v[162:163], off nt
	global_load_dword v146, v[164:165], off offset:64
	global_load_dwordx4 v[140:143], v[162:163], off offset:2048 nt
	global_load_dword v147, v[164:165], off offset:96
	s_waitcnt vmcnt(24)
	v_cmp_lt_i32_e64 s[8:9], 0, v56
	v_cmp_lt_i32_e64 s[22:23], 1, v56
	v_cmp_lt_i32_e64 s[24:25], 2, v56
	v_mov_b32_e32 v8, 0
	v_mov_b32_e32 v9, 0
	v_mov_b32_e32 v10, 0
	v_mov_b32_e32 v11, 0
	v_mov_b32_e32 v12, 0
	v_mov_b32_e32 v13, 0
	v_mov_b32_e32 v14, 0
	v_mov_b32_e32 v15, 0
	v_cndmask_b32_e64 v32, 0, v32, s[8:9]
	v_cndmask_b32_e64 v33, 0, v33, s[8:9]
	v_cndmask_b32_e64 v34, 0, v34, s[8:9]
	v_cndmask_b32_e64 v35, 0, v35, s[8:9]
	v_cndmask_b32_e64 v48, 0, v48, s[8:9]
	v_cndmask_b32_e64 v36, 0, v36, s[22:23]
	v_cndmask_b32_e64 v37, 0, v37, s[22:23]
	v_cndmask_b32_e64 v38, 0, v38, s[22:23]
	v_cndmask_b32_e64 v39, 0, v39, s[22:23]
	v_cndmask_b32_e64 v49, 0, v49, s[22:23]
	v_cndmask_b32_e64 v40, 0, v40, s[24:25]
	v_cndmask_b32_e64 v41, 0, v41, s[24:25]
	v_cndmask_b32_e64 v42, 0, v42, s[24:25]
	v_cndmask_b32_e64 v43, 0, v43, s[24:25]
	v_cndmask_b32_e64 v50, 0, v50, s[24:25]
	v_mov_b32_e32 v1, 0
	v_lshlrev_b32_e32 v166, 16, v32
	v_and_b32_e32 v167, 0xffff0000, v32
	v_lshlrev_b32_e32 v168, 16, v33
	v_and_b32_e32 v169, 0xffff0000, v33
	v_lshlrev_b32_e32 v170, 16, v34
	v_and_b32_e32 v171, 0xffff0000, v34
	v_lshlrev_b32_e32 v172, 16, v35
	v_and_b32_e32 v173, 0xffff0000, v35
	v_pk_add_f32 v[8:9], v[8:9], v[166:167]
	v_pk_add_f32 v[10:11], v[10:11], v[168:169]
	v_pk_add_f32 v[12:13], v[12:13], v[170:171]
	v_pk_add_f32 v[14:15], v[14:15], v[172:173]
	v_add_f32_e32 v1, v1, v48
	v_lshlrev_b32_e32 v166, 16, v36
	v_and_b32_e32 v167, 0xffff0000, v36
	v_lshlrev_b32_e32 v168, 16, v37
	v_and_b32_e32 v169, 0xffff0000, v37
	v_lshlrev_b32_e32 v170, 16, v38
	v_and_b32_e32 v171, 0xffff0000, v38
	v_lshlrev_b32_e32 v172, 16, v39
	v_and_b32_e32 v173, 0xffff0000, v39
	v_pk_add_f32 v[8:9], v[8:9], v[166:167]
	v_pk_add_f32 v[10:11], v[10:11], v[168:169]
	v_pk_add_f32 v[12:13], v[12:13], v[170:171]
	v_pk_add_f32 v[14:15], v[14:15], v[172:173]
	v_add_f32_e32 v1, v1, v49
	v_lshlrev_b32_e32 v166, 16, v40
	v_and_b32_e32 v167, 0xffff0000, v40
	v_lshlrev_b32_e32 v168, 16, v41
	v_and_b32_e32 v169, 0xffff0000, v41
	v_lshlrev_b32_e32 v170, 16, v42
	v_and_b32_e32 v171, 0xffff0000, v42
	v_lshlrev_b32_e32 v172, 16, v43
	v_and_b32_e32 v173, 0xffff0000, v43
	v_pk_add_f32 v[8:9], v[8:9], v[166:167]
	v_pk_add_f32 v[10:11], v[10:11], v[168:169]
	v_pk_add_f32 v[12:13], v[12:13], v[170:171]
	v_pk_add_f32 v[14:15], v[14:15], v[172:173]
	v_add_f32_e32 v1, v1, v50
	v_lshlrev_b32_e32 v166, 16, v44
	v_and_b32_e32 v167, 0xffff0000, v44
	v_lshlrev_b32_e32 v168, 16, v45
	v_and_b32_e32 v169, 0xffff0000, v45
	v_lshlrev_b32_e32 v170, 16, v46
	v_and_b32_e32 v171, 0xffff0000, v46
	v_lshlrev_b32_e32 v172, 16, v47
	v_and_b32_e32 v173, 0xffff0000, v47
	v_pk_add_f32 v[8:9], v[8:9], v[166:167]
	v_pk_add_f32 v[10:11], v[10:11], v[168:169]
	v_pk_add_f32 v[12:13], v[12:13], v[170:171]
	v_pk_add_f32 v[14:15], v[14:15], v[172:173]
	v_add_f32_e32 v1, v1, v51
	v_div_scale_f32 v21, s[8:9], v1, v1, 1.0
	v_rcp_f32_e32 v16, v21
	v_div_scale_f32 v28, vcc, 1.0, v1, 1.0
	v_fma_f32 v17, -v21, v16, 1.0
	v_fmac_f32_e32 v16, v17, v16
	v_mul_f32_e32 v17, v28, v16
	v_fma_f32 v22, -v21, v17, v28
	v_fmac_f32_e32 v17, v22, v16
	v_fma_f32 v21, -v21, v17, v28
	v_div_fmas_f32 v16, v21, v16, v17
	v_div_fixup_f32 v16, v16, v1, 1.0
	v_pk_mul_f32 v[8:9], v[16:17], v[8:9] op_sel_hi:[0,1]
	v_pk_mul_f32 v[10:11], v[16:17], v[10:11] op_sel_hi:[0,1]
	v_pk_mul_f32 v[12:13], v[16:17], v[12:13] op_sel_hi:[0,1]
	v_pk_mul_f32 v[14:15], v[16:17], v[14:15] op_sel_hi:[0,1]
	v_lshlrev_b64 v[160:161], 12, v[54:55]
	v_cvt_pk_bf16_f32 v24, v8, v9
	v_cvt_pk_bf16_f32 v25, v10, v11
	v_cvt_pk_bf16_f32 v26, v12, v13
	v_cvt_pk_bf16_f32 v27, v14, v15
	v_lshl_add_u64 v[160:161], v[6:7], 0, v[160:161]
	s_and_saveexec_b64 s[4:5], s[14:15]
	global_store_dwordx4 v[160:161], v[24:27], off
	s_mov_b64 exec, s[4:5]
	s_waitcnt vmcnt(17)
	v_cmp_lt_i32_e64 s[8:9], 0, v88
	v_cmp_lt_i32_e64 s[22:23], 1, v88
	v_cmp_lt_i32_e64 s[24:25], 2, v88
	v_mov_b32_e32 v8, 0
	v_mov_b32_e32 v9, 0
	v_mov_b32_e32 v10, 0
	v_mov_b32_e32 v11, 0
	v_mov_b32_e32 v12, 0
	v_mov_b32_e32 v13, 0
	v_mov_b32_e32 v14, 0
	v_mov_b32_e32 v15, 0
	v_cndmask_b32_e64 v64, 0, v64, s[8:9]
	v_cndmask_b32_e64 v65, 0, v65, s[8:9]
	v_cndmask_b32_e64 v66, 0, v66, s[8:9]
	v_cndmask_b32_e64 v67, 0, v67, s[8:9]
	v_cndmask_b32_e64 v80, 0, v80, s[8:9]
	v_cndmask_b32_e64 v68, 0, v68, s[22:23]
	v_cndmask_b32_e64 v69, 0, v69, s[22:23]
	v_cndmask_b32_e64 v70, 0, v70, s[22:23]
	v_cndmask_b32_e64 v71, 0, v71, s[22:23]
	v_cndmask_b32_e64 v81, 0, v81, s[22:23]
	v_cndmask_b32_e64 v72, 0, v72, s[24:25]
	v_cndmask_b32_e64 v73, 0, v73, s[24:25]
	v_cndmask_b32_e64 v74, 0, v74, s[24:25]
	v_cndmask_b32_e64 v75, 0, v75, s[24:25]
	v_cndmask_b32_e64 v82, 0, v82, s[24:25]
	v_mov_b32_e32 v1, 0
	v_lshlrev_b32_e32 v166, 16, v64
	v_and_b32_e32 v167, 0xffff0000, v64
	v_lshlrev_b32_e32 v168, 16, v65
	v_and_b32_e32 v169, 0xffff0000, v65
	v_lshlrev_b32_e32 v170, 16, v66
	v_and_b32_e32 v171, 0xffff0000, v66
	v_lshlrev_b32_e32 v172, 16, v67
	v_and_b32_e32 v173, 0xffff0000, v67
	v_pk_add_f32 v[8:9], v[8:9], v[166:167]
	v_pk_add_f32 v[10:11], v[10:11], v[168:169]
	v_pk_add_f32 v[12:13], v[12:13], v[170:171]
	v_pk_add_f32 v[14:15], v[14:15], v[172:173]
	v_add_f32_e32 v1, v1, v80
	v_lshlrev_b32_e32 v166, 16, v68
	v_and_b32_e32 v167, 0xffff0000, v68
	v_lshlrev_b32_e32 v168, 16, v69
	v_and_b32_e32 v169, 0xffff0000, v69
	v_lshlrev_b32_e32 v170, 16, v70
	v_and_b32_e32 v171, 0xffff0000, v70
	v_lshlrev_b32_e32 v172, 16, v71
	v_and_b32_e32 v173, 0xffff0000, v71
	v_pk_add_f32 v[8:9], v[8:9], v[166:167]
	v_pk_add_f32 v[10:11], v[10:11], v[168:169]
	v_pk_add_f32 v[12:13], v[12:13], v[170:171]
	v_pk_add_f32 v[14:15], v[14:15], v[172:173]
	v_add_f32_e32 v1, v1, v81
	v_lshlrev_b32_e32 v166, 16, v72
	v_and_b32_e32 v167, 0xffff0000, v72
	v_lshlrev_b32_e32 v168, 16, v73
	v_and_b32_e32 v169, 0xffff0000, v73
	v_lshlrev_b32_e32 v170, 16, v74
	v_and_b32_e32 v171, 0xffff0000, v74
	v_lshlrev_b32_e32 v172, 16, v75
	v_and_b32_e32 v173, 0xffff0000, v75
	v_pk_add_f32 v[8:9], v[8:9], v[166:167]
	v_pk_add_f32 v[10:11], v[10:11], v[168:169]
	v_pk_add_f32 v[12:13], v[12:13], v[170:171]
	v_pk_add_f32 v[14:15], v[14:15], v[172:173]
	v_add_f32_e32 v1, v1, v82
	v_lshlrev_b32_e32 v166, 16, v76
	v_and_b32_e32 v167, 0xffff0000, v76
	v_lshlrev_b32_e32 v168, 16, v77
	v_and_b32_e32 v169, 0xffff0000, v77
	v_lshlrev_b32_e32 v170, 16, v78
	v_and_b32_e32 v171, 0xffff0000, v78
	v_lshlrev_b32_e32 v172, 16, v79
	v_and_b32_e32 v173, 0xffff0000, v79
	v_pk_add_f32 v[8:9], v[8:9], v[166:167]
	v_pk_add_f32 v[10:11], v[10:11], v[168:169]
	v_pk_add_f32 v[12:13], v[12:13], v[170:171]
	v_pk_add_f32 v[14:15], v[14:15], v[172:173]
	v_add_f32_e32 v1, v1, v83
	v_div_scale_f32 v21, s[8:9], v1, v1, 1.0
	v_rcp_f32_e32 v16, v21
	v_div_scale_f32 v28, vcc, 1.0, v1, 1.0
	v_fma_f32 v17, -v21, v16, 1.0
	v_fmac_f32_e32 v16, v17, v16
	v_mul_f32_e32 v17, v28, v16
	v_fma_f32 v22, -v21, v17, v28
	v_fmac_f32_e32 v17, v22, v16
	v_fma_f32 v21, -v21, v17, v28
	v_div_fmas_f32 v16, v21, v16, v17
	v_div_fixup_f32 v16, v16, v1, 1.0
	v_pk_mul_f32 v[8:9], v[16:17], v[8:9] op_sel_hi:[0,1]
	v_pk_mul_f32 v[10:11], v[16:17], v[10:11] op_sel_hi:[0,1]
	v_pk_mul_f32 v[12:13], v[16:17], v[12:13] op_sel_hi:[0,1]
	v_pk_mul_f32 v[14:15], v[16:17], v[14:15] op_sel_hi:[0,1]
	v_lshlrev_b64 v[160:161], 12, v[86:87]
	v_cvt_pk_bf16_f32 v24, v8, v9
	v_cvt_pk_bf16_f32 v25, v10, v11
	v_cvt_pk_bf16_f32 v26, v12, v13
	v_cvt_pk_bf16_f32 v27, v14, v15
	v_lshl_add_u64 v[160:161], v[6:7], 0, v[160:161]
	s_and_saveexec_b64 s[4:5], s[16:17]
	global_store_dwordx4 v[160:161], v[24:27], off
	s_mov_b64 exec, s[4:5]
	s_waitcnt vmcnt(10)
	v_cmp_lt_i32_e64 s[8:9], 0, v120
	v_cmp_lt_i32_e64 s[22:23], 1, v120
	v_cmp_lt_i32_e64 s[24:25], 2, v120
	v_mov_b32_e32 v8, 0
	v_mov_b32_e32 v9, 0
	v_mov_b32_e32 v10, 0
	v_mov_b32_e32 v11, 0
	v_mov_b32_e32 v12, 0
	v_mov_b32_e32 v13, 0
	v_mov_b32_e32 v14, 0
	v_mov_b32_e32 v15, 0
	v_cndmask_b32_e64 v96, 0, v96, s[8:9]
	v_cndmask_b32_e64 v97, 0, v97, s[8:9]
	v_cndmask_b32_e64 v98, 0, v98, s[8:9]
	v_cndmask_b32_e64 v99, 0, v99, s[8:9]
	v_cndmask_b32_e64 v112, 0, v112, s[8:9]
	v_cndmask_b32_e64 v100, 0, v100, s[22:23]
	v_cndmask_b32_e64 v101, 0, v101, s[22:23]
	v_cndmask_b32_e64 v102, 0, v102, s[22:23]
	v_cndmask_b32_e64 v103, 0, v103, s[22:23]
	v_cndmask_b32_e64 v113, 0, v113, s[22:23]
	v_cndmask_b32_e64 v104, 0, v104, s[24:25]
	v_cndmask_b32_e64 v105, 0, v105, s[24:25]
	v_cndmask_b32_e64 v106, 0, v106, s[24:25]
	v_cndmask_b32_e64 v107, 0, v107, s[24:25]
	v_cndmask_b32_e64 v114, 0, v114, s[24:25]
	v_mov_b32_e32 v1, 0
	v_lshlrev_b32_e32 v166, 16, v96
	v_and_b32_e32 v167, 0xffff0000, v96
	v_lshlrev_b32_e32 v168, 16, v97
	v_and_b32_e32 v169, 0xffff0000, v97
	v_lshlrev_b32_e32 v170, 16, v98
	v_and_b32_e32 v171, 0xffff0000, v98
	v_lshlrev_b32_e32 v172, 16, v99
	v_and_b32_e32 v173, 0xffff0000, v99
	v_pk_add_f32 v[8:9], v[8:9], v[166:167]
	v_pk_add_f32 v[10:11], v[10:11], v[168:169]
	v_pk_add_f32 v[12:13], v[12:13], v[170:171]
	v_pk_add_f32 v[14:15], v[14:15], v[172:173]
	v_add_f32_e32 v1, v1, v112
	v_lshlrev_b32_e32 v166, 16, v100
	v_and_b32_e32 v167, 0xffff0000, v100
	v_lshlrev_b32_e32 v168, 16, v101
	v_and_b32_e32 v169, 0xffff0000, v101
	v_lshlrev_b32_e32 v170, 16, v102
	v_and_b32_e32 v171, 0xffff0000, v102
	v_lshlrev_b32_e32 v172, 16, v103
	v_and_b32_e32 v173, 0xffff0000, v103
	v_pk_add_f32 v[8:9], v[8:9], v[166:167]
	v_pk_add_f32 v[10:11], v[10:11], v[168:169]
	v_pk_add_f32 v[12:13], v[12:13], v[170:171]
	v_pk_add_f32 v[14:15], v[14:15], v[172:173]
	v_add_f32_e32 v1, v1, v113
	v_lshlrev_b32_e32 v166, 16, v104
	v_and_b32_e32 v167, 0xffff0000, v104
	v_lshlrev_b32_e32 v168, 16, v105
	v_and_b32_e32 v169, 0xffff0000, v105
	v_lshlrev_b32_e32 v170, 16, v106
	v_and_b32_e32 v171, 0xffff0000, v106
	v_lshlrev_b32_e32 v172, 16, v107
	v_and_b32_e32 v173, 0xffff0000, v107
	v_pk_add_f32 v[8:9], v[8:9], v[166:167]
	v_pk_add_f32 v[10:11], v[10:11], v[168:169]
	v_pk_add_f32 v[12:13], v[12:13], v[170:171]
	v_pk_add_f32 v[14:15], v[14:15], v[172:173]
	v_add_f32_e32 v1, v1, v114
	v_lshlrev_b32_e32 v166, 16, v108
	v_and_b32_e32 v167, 0xffff0000, v108
	v_lshlrev_b32_e32 v168, 16, v109
	v_and_b32_e32 v169, 0xffff0000, v109
	v_lshlrev_b32_e32 v170, 16, v110
	v_and_b32_e32 v171, 0xffff0000, v110
	v_lshlrev_b32_e32 v172, 16, v111
	v_and_b32_e32 v173, 0xffff0000, v111
	v_pk_add_f32 v[8:9], v[8:9], v[166:167]
	v_pk_add_f32 v[10:11], v[10:11], v[168:169]
	v_pk_add_f32 v[12:13], v[12:13], v[170:171]
	v_pk_add_f32 v[14:15], v[14:15], v[172:173]
	v_add_f32_e32 v1, v1, v115
	v_div_scale_f32 v21, s[8:9], v1, v1, 1.0
	v_rcp_f32_e32 v16, v21
	v_div_scale_f32 v28, vcc, 1.0, v1, 1.0
	v_fma_f32 v17, -v21, v16, 1.0
	v_fmac_f32_e32 v16, v17, v16
	v_mul_f32_e32 v17, v28, v16
	v_fma_f32 v22, -v21, v17, v28
	v_fmac_f32_e32 v17, v22, v16
	v_fma_f32 v21, -v21, v17, v28
	v_div_fmas_f32 v16, v21, v16, v17
	v_div_fixup_f32 v16, v16, v1, 1.0
	v_pk_mul_f32 v[8:9], v[16:17], v[8:9] op_sel_hi:[0,1]
	v_pk_mul_f32 v[10:11], v[16:17], v[10:11] op_sel_hi:[0,1]
	v_pk_mul_f32 v[12:13], v[16:17], v[12:13] op_sel_hi:[0,1]
	v_pk_mul_f32 v[14:15], v[16:17], v[14:15] op_sel_hi:[0,1]
	v_lshlrev_b64 v[160:161], 12, v[118:119]
	v_cvt_pk_bf16_f32 v24, v8, v9
	v_cvt_pk_bf16_f32 v25, v10, v11
	v_cvt_pk_bf16_f32 v26, v12, v13
	v_cvt_pk_bf16_f32 v27, v14, v15
	v_lshl_add_u64 v[160:161], v[6:7], 0, v[160:161]
	s_and_saveexec_b64 s[4:5], s[18:19]
	global_store_dwordx4 v[160:161], v[24:27], off
	s_mov_b64 exec, s[4:5]
	s_waitcnt vmcnt(3)
	v_cmp_lt_i32_e64 s[8:9], 0, v152
	v_cmp_lt_i32_e64 s[22:23], 1, v152
	v_cmp_lt_i32_e64 s[24:25], 2, v152
	v_mov_b32_e32 v8, 0
	v_mov_b32_e32 v9, 0
	v_mov_b32_e32 v10, 0
	v_mov_b32_e32 v11, 0
	v_mov_b32_e32 v12, 0
	v_mov_b32_e32 v13, 0
	v_mov_b32_e32 v14, 0
	v_mov_b32_e32 v15, 0
	v_cndmask_b32_e64 v128, 0, v128, s[8:9]
	v_cndmask_b32_e64 v129, 0, v129, s[8:9]
	v_cndmask_b32_e64 v130, 0, v130, s[8:9]
	v_cndmask_b32_e64 v131, 0, v131, s[8:9]
	v_cndmask_b32_e64 v144, 0, v144, s[8:9]
	v_cndmask_b32_e64 v132, 0, v132, s[22:23]
	v_cndmask_b32_e64 v133, 0, v133, s[22:23]
	v_cndmask_b32_e64 v134, 0, v134, s[22:23]
	v_cndmask_b32_e64 v135, 0, v135, s[22:23]
	v_cndmask_b32_e64 v145, 0, v145, s[22:23]
	v_cndmask_b32_e64 v136, 0, v136, s[24:25]
	v_cndmask_b32_e64 v137, 0, v137, s[24:25]
	v_cndmask_b32_e64 v138, 0, v138, s[24:25]
	v_cndmask_b32_e64 v139, 0, v139, s[24:25]
	v_cndmask_b32_e64 v146, 0, v146, s[24:25]
	v_mov_b32_e32 v1, 0
	v_lshlrev_b32_e32 v166, 16, v128
	v_and_b32_e32 v167, 0xffff0000, v128
	v_lshlrev_b32_e32 v168, 16, v129
	v_and_b32_e32 v169, 0xffff0000, v129
	v_lshlrev_b32_e32 v170, 16, v130
	v_and_b32_e32 v171, 0xffff0000, v130
	v_lshlrev_b32_e32 v172, 16, v131
	v_and_b32_e32 v173, 0xffff0000, v131
	v_pk_add_f32 v[8:9], v[8:9], v[166:167]
	v_pk_add_f32 v[10:11], v[10:11], v[168:169]
	v_pk_add_f32 v[12:13], v[12:13], v[170:171]
	v_pk_add_f32 v[14:15], v[14:15], v[172:173]
	v_add_f32_e32 v1, v1, v144
	v_lshlrev_b32_e32 v166, 16, v132
	v_and_b32_e32 v167, 0xffff0000, v132
	v_lshlrev_b32_e32 v168, 16, v133
	v_and_b32_e32 v169, 0xffff0000, v133
	v_lshlrev_b32_e32 v170, 16, v134
	v_and_b32_e32 v171, 0xffff0000, v134
	v_lshlrev_b32_e32 v172, 16, v135
	v_and_b32_e32 v173, 0xffff0000, v135
	v_pk_add_f32 v[8:9], v[8:9], v[166:167]
	v_pk_add_f32 v[10:11], v[10:11], v[168:169]
	v_pk_add_f32 v[12:13], v[12:13], v[170:171]
	v_pk_add_f32 v[14:15], v[14:15], v[172:173]
	v_add_f32_e32 v1, v1, v145
	v_lshlrev_b32_e32 v166, 16, v136
	v_and_b32_e32 v167, 0xffff0000, v136
	v_lshlrev_b32_e32 v168, 16, v137
	v_and_b32_e32 v169, 0xffff0000, v137
	v_lshlrev_b32_e32 v170, 16, v138
	v_and_b32_e32 v171, 0xffff0000, v138
	v_lshlrev_b32_e32 v172, 16, v139
	v_and_b32_e32 v173, 0xffff0000, v139
	v_pk_add_f32 v[8:9], v[8:9], v[166:167]
	v_pk_add_f32 v[10:11], v[10:11], v[168:169]
	v_pk_add_f32 v[12:13], v[12:13], v[170:171]
	v_pk_add_f32 v[14:15], v[14:15], v[172:173]
	v_add_f32_e32 v1, v1, v146
	v_lshlrev_b32_e32 v166, 16, v140
	v_and_b32_e32 v167, 0xffff0000, v140
	v_lshlrev_b32_e32 v168, 16, v141
	v_and_b32_e32 v169, 0xffff0000, v141
	v_lshlrev_b32_e32 v170, 16, v142
	v_and_b32_e32 v171, 0xffff0000, v142
	v_lshlrev_b32_e32 v172, 16, v143
	v_and_b32_e32 v173, 0xffff0000, v143
	v_pk_add_f32 v[8:9], v[8:9], v[166:167]
	v_pk_add_f32 v[10:11], v[10:11], v[168:169]
	v_pk_add_f32 v[12:13], v[12:13], v[170:171]
	v_pk_add_f32 v[14:15], v[14:15], v[172:173]
	v_add_f32_e32 v1, v1, v147
	v_div_scale_f32 v21, s[8:9], v1, v1, 1.0
	v_rcp_f32_e32 v16, v21
	v_div_scale_f32 v28, vcc, 1.0, v1, 1.0
	v_fma_f32 v17, -v21, v16, 1.0
	v_fmac_f32_e32 v16, v17, v16
	v_mul_f32_e32 v17, v28, v16
	v_fma_f32 v22, -v21, v17, v28
	v_fmac_f32_e32 v17, v22, v16
	v_fma_f32 v21, -v21, v17, v28
	v_div_fmas_f32 v16, v21, v16, v17
	v_div_fixup_f32 v16, v16, v1, 1.0
	v_pk_mul_f32 v[8:9], v[16:17], v[8:9] op_sel_hi:[0,1]
	v_pk_mul_f32 v[10:11], v[16:17], v[10:11] op_sel_hi:[0,1]
	v_pk_mul_f32 v[12:13], v[16:17], v[12:13] op_sel_hi:[0,1]
	v_pk_mul_f32 v[14:15], v[16:17], v[14:15] op_sel_hi:[0,1]
	v_lshlrev_b64 v[160:161], 12, v[150:151]
	v_cvt_pk_bf16_f32 v24, v8, v9
	v_cvt_pk_bf16_f32 v25, v10, v11
	v_cvt_pk_bf16_f32 v26, v12, v13
	v_cvt_pk_bf16_f32 v27, v14, v15
	v_lshl_add_u64 v[160:161], v[6:7], 0, v[160:161]
	s_and_saveexec_b64 s[4:5], s[20:21]
	global_store_dwordx4 v[160:161], v[24:27], off
	s_mov_b64 exec, s[4:5]
	s_lshl_b32 s12, s11, 2
	v_add_u32_e32 v20, s12, v20
	v_cmp_le_i32_e32 vcc, s10, v20
	s_or_b64 s[2:3], vcc, s[2:3]
	s_andn2_b64 exec, exec, s[2:3]
	s_cbranch_execnz .Lc4_outer

.LBB0_1216:
	v_lshl_or_b32 v98, s11, 2, v193
	v_mad_u64_u32 v[144:145], s[46:47], v98, s65, v[96:97]
	ds_read_b128 v[100:103], v144
	s_waitcnt lgkmcnt(3)
	ds_read_b128 v[104:107], v144 offset:512
	s_waitcnt lgkmcnt(2)
	ds_read_b128 v[108:111], v144 offset:1040
	ds_read_b128 v[112:115], v144 offset:1552
	ds_read_b128 v[116:119], v144 offset:2080
	ds_read_b128 v[120:123], v144 offset:2592
	ds_read_b128 v[124:127], v144 offset:3120
	ds_read_b128 v[128:131], v144 offset:3632
	s_waitcnt lgkmcnt(7)
	v_pk_fma_f32 v[100:101], v[64:65], v[100:101], v[76:77]
	v_pk_fma_f32 v[102:103], v[66:67], v[102:103], v[78:79]
	s_waitcnt lgkmcnt(5)
	v_pk_fma_f32 v[100:101], v[68:69], v[108:109], v[100:101]
	v_pk_fma_f32 v[102:103], v[70:71], v[110:111], v[102:103]
	s_waitcnt lgkmcnt(3)
	v_pk_fma_f32 v[100:101], v[72:73], v[116:117], v[100:101]
	v_pk_fma_f32 v[102:103], v[74:75], v[118:119], v[102:103]
	v_mul_f32_e32 v99, 0xbfb8aa3b, v100
	v_exp_f32_e32 v99, v99
	v_mul_f32_e32 v132, 0xbfb8aa3b, v101
	v_exp_f32_e32 v140, v132
	v_pk_fma_f32 v[104:105], v[80:81], v[104:105], v[92:93]
	v_add_f32_e32 v99, 1.0, v99
	v_rcp_f32_e32 v148, v99
	v_add_f32_e32 v99, 1.0, v140
	v_rcp_f32_e32 v149, v99
	v_mul_f32_e32 v99, 0xbfb8aa3b, v102
	v_exp_f32_e32 v99, v99
	v_pk_fma_f32 v[104:105], v[84:85], v[112:113], v[104:105]
	v_pk_mul_f32 v[100:101], v[100:101], v[148:149]
	v_mul_f32_e32 v148, 0xbfb8aa3b, v103
	v_exp_f32_e32 v149, v148
	v_pk_fma_f32 v[106:107], v[82:83], v[106:107], v[94:95]
	s_waitcnt lgkmcnt(2)
	v_pk_fma_f32 v[104:105], v[88:89], v[120:121], v[104:105]
	v_add_f32_e32 v99, 1.0, v99
	v_pk_mul_f32 v[100:101], v[104:105], v[100:101]
	v_pk_fma_f32 v[104:105], v[86:87], v[114:115], v[106:107]
	v_pk_fma_f32 v[106:107], v[64:65], v[108:109], v[76:77]
	v_rcp_f32_e32 v148, v99
	v_pk_fma_f32 v[106:107], v[68:69], v[116:117], v[106:107]
	v_add_f32_e32 v99, 1.0, v149
	s_waitcnt lgkmcnt(1)
	v_pk_fma_f32 v[106:107], v[72:73], v[124:125], v[106:107]
	v_rcp_f32_e32 v149, v99
	v_mul_f32_e32 v99, 0xbfb8aa3b, v106
	v_exp_f32_e32 v99, v99
	v_mul_f32_e32 v108, 0xbfb8aa3b, v107
	v_exp_f32_e32 v109, v108
	v_pk_mul_f32 v[102:103], v[102:103], v[148:149]
	v_add_f32_e32 v99, 1.0, v99
	v_pk_fma_f32 v[104:105], v[90:91], v[122:123], v[104:105]
	v_rcp_f32_e32 v108, v99
	v_add_f32_e32 v99, 1.0, v109
	v_rcp_f32_e32 v109, v99
	v_pk_mul_f32 v[102:103], v[104:105], v[102:103]
	v_pk_fma_f32 v[104:105], v[66:67], v[110:111], v[78:79]
	v_cvt_pk_bf16_f32 v99, v100, v101
	v_pk_fma_f32 v[104:105], v[70:71], v[118:119], v[104:105]
	v_cvt_pk_bf16_f32 v100, v102, v103
	v_pk_fma_f32 v[104:105], v[74:75], v[126:127], v[104:105]
	v_pk_mul_f32 v[102:103], v[106:107], v[108:109]
	v_mul_f32_e32 v101, 0xbfb8aa3b, v104
	v_exp_f32_e32 v101, v101
	v_mul_f32_e32 v106, 0xbfb8aa3b, v105
	v_exp_f32_e32 v109, v106
	ds_read_b128 v[132:135], v144 offset:4160
	ds_read_b128 v[136:139], v144 offset:4672
	v_add_f32_e32 v101, 1.0, v101
	v_rcp_f32_e32 v108, v101
	v_add_f32_e32 v101, 1.0, v109
	v_rcp_f32_e32 v109, v101
	v_pk_fma_f32 v[106:107], v[80:81], v[112:113], v[92:93]
	ds_read_b128 v[140:143], v144 offset:5200
	ds_read_b128 v[144:147], v144 offset:5712
	v_pk_fma_f32 v[106:107], v[84:85], v[120:121], v[106:107]
	v_pk_mul_f32 v[104:105], v[104:105], v[108:109]
	v_pk_fma_f32 v[108:109], v[64:65], v[116:117], v[76:77]
	s_waitcnt lgkmcnt(4)
	v_pk_fma_f32 v[106:107], v[88:89], v[128:129], v[106:107]
	v_pk_fma_f32 v[108:109], v[68:69], v[124:125], v[108:109]
	v_pk_mul_f32 v[102:103], v[106:107], v[102:103]
	s_waitcnt lgkmcnt(3)
	v_pk_fma_f32 v[108:109], v[72:73], v[132:133], v[108:109]
	v_pk_fma_f32 v[106:107], v[82:83], v[114:115], v[94:95]
	v_mul_f32_e32 v101, 0xbfb8aa3b, v108
	v_exp_f32_e32 v101, v101
	v_mul_f32_e32 v110, 0xbfb8aa3b, v109
	v_exp_f32_e32 v111, v110
	v_pk_fma_f32 v[106:107], v[86:87], v[122:123], v[106:107]
	v_add_f32_e32 v101, 1.0, v101
	v_pk_fma_f32 v[106:107], v[90:91], v[130:131], v[106:107]
	v_rcp_f32_e32 v110, v101
	v_add_f32_e32 v101, 1.0, v111
	v_rcp_f32_e32 v111, v101
	v_pk_mul_f32 v[104:105], v[106:107], v[104:105]
	v_pk_fma_f32 v[106:107], v[66:67], v[118:119], v[78:79]
	v_cvt_pk_bf16_f32 v101, v102, v103
	v_pk_fma_f32 v[106:107], v[70:71], v[126:127], v[106:107]
	v_cvt_pk_bf16_f32 v102, v104, v105
	v_pk_fma_f32 v[106:107], v[74:75], v[134:135], v[106:107]
	v_pk_mul_f32 v[104:105], v[108:109], v[110:111]
	v_mul_f32_e32 v103, 0xbfb8aa3b, v106
	v_exp_f32_e32 v103, v103
	v_mul_f32_e32 v108, 0xbfb8aa3b, v107
	v_exp_f32_e32 v111, v108
	v_pk_fma_f32 v[108:109], v[80:81], v[120:121], v[92:93]
	v_add_f32_e32 v103, 1.0, v103
	v_rcp_f32_e32 v110, v103
	v_add_f32_e32 v103, 1.0, v111
	v_rcp_f32_e32 v111, v103
	v_pk_fma_f32 v[108:109], v[84:85], v[128:129], v[108:109]
	v_pk_mul_f32 v[106:107], v[106:107], v[110:111]
	v_pk_fma_f32 v[110:111], v[64:65], v[124:125], v[76:77]
	s_waitcnt lgkmcnt(2)
	v_pk_fma_f32 v[108:109], v[88:89], v[136:137], v[108:109]
	v_pk_fma_f32 v[110:111], v[68:69], v[132:133], v[110:111]
	v_pk_mul_f32 v[104:105], v[108:109], v[104:105]
	s_waitcnt lgkmcnt(1)
	v_pk_fma_f32 v[110:111], v[72:73], v[140:141], v[110:111]
	v_pk_fma_f32 v[108:109], v[82:83], v[122:123], v[94:95]
	v_mul_f32_e32 v103, 0xbfb8aa3b, v110
	v_exp_f32_e32 v103, v103
	v_mul_f32_e32 v112, 0xbfb8aa3b, v111
	v_exp_f32_e32 v113, v112
	v_pk_fma_f32 v[108:109], v[86:87], v[130:131], v[108:109]
	v_add_f32_e32 v103, 1.0, v103
	v_pk_fma_f32 v[108:109], v[90:91], v[138:139], v[108:109]
	v_rcp_f32_e32 v112, v103
	v_add_f32_e32 v103, 1.0, v113
	v_rcp_f32_e32 v113, v103
	v_pk_mul_f32 v[106:107], v[108:109], v[106:107]
	v_pk_fma_f32 v[108:109], v[66:67], v[126:127], v[78:79]
	v_cvt_pk_bf16_f32 v103, v104, v105
	v_pk_fma_f32 v[108:109], v[70:71], v[134:135], v[108:109]
	v_cvt_pk_bf16_f32 v104, v106, v107
	v_pk_fma_f32 v[108:109], v[74:75], v[142:143], v[108:109]
	v_pk_mul_f32 v[106:107], v[110:111], v[112:113]
	v_mul_f32_e32 v105, 0xbfb8aa3b, v108
	v_exp_f32_e32 v105, v105
	v_mul_f32_e32 v110, 0xbfb8aa3b, v109
	v_exp_f32_e32 v113, v110
	v_pk_fma_f32 v[110:111], v[80:81], v[128:129], v[92:93]
	v_add_f32_e32 v105, 1.0, v105
	v_rcp_f32_e32 v112, v105
	v_add_f32_e32 v105, 1.0, v113
	v_rcp_f32_e32 v113, v105
	v_pk_fma_f32 v[110:111], v[84:85], v[136:137], v[110:111]
	v_cndmask_b32_e64 v105, v99, v103, s[6:7]
	s_waitcnt lgkmcnt(0)
	v_pk_fma_f32 v[110:111], v[88:89], v[144:145], v[110:111]
	v_pk_mul_f32 v[108:109], v[108:109], v[112:113]
	v_pk_mul_f32 v[106:107], v[110:111], v[106:107]
	v_pk_fma_f32 v[110:111], v[82:83], v[130:131], v[94:95]
	v_cvt_pk_bf16_f32 v107, v106, v107
	v_pk_fma_f32 v[110:111], v[86:87], v[138:139], v[110:111]
	v_cndmask_b32_e64 v106, v100, v104, s[6:7]
	v_pk_fma_f32 v[110:111], v[90:91], v[146:147], v[110:111]
	ds_bpermute_b32 v105, v97, v105
	v_pk_mul_f32 v[108:109], v[110:111], v[108:109]
	ds_bpermute_b32 v106, v97, v106
	v_cvt_pk_bf16_f32 v108, v108, v109
	v_cndmask_b32_e64 v110, v102, v108, s[6:7]
	v_cndmask_b32_e64 v109, v101, v107, s[6:7]
	ds_bpermute_b32 v109, v97, v109
	ds_bpermute_b32 v110, v97, v110
	v_or_b32_e32 v111, s11, v200
	v_cmp_ne_u32_e32 vcc, 0, v111
	s_or_b64 s[48:49], s[8:9], vcc
	s_and_saveexec_b64 s[46:47], s[48:49]
	s_cbranch_execz .LBB0_1215
	v_cndmask_b32_e64 v101, v107, v101, s[6:7]
	v_cndmask_b32_e64 v102, v108, v102, s[6:7]
	v_cndmask_b32_e64 v99, v103, v99, s[6:7]
	v_cndmask_b32_e64 v100, v104, v100, s[6:7]
	s_waitcnt lgkmcnt(0)
	v_cndmask_b32_e64 v113, v102, v110, s[6:7]
	v_cndmask_b32_e64 v112, v101, v109, s[6:7]
	v_cndmask_b32_e64 v111, v110, v102, s[6:7]
	v_cndmask_b32_e64 v110, v109, v101, s[6:7]
	v_cndmask_b32_e64 v103, v100, v106, s[6:7]
	v_cndmask_b32_e64 v102, v99, v105, s[6:7]
	v_cndmask_b32_e64 v101, v106, v100, s[6:7]
	v_cndmask_b32_e64 v100, v105, v99, s[6:7]
	v_add_u32_e32 v104, v98, v195
	v_mov_b64_e32 v[98:99], s[80:81]
	v_mad_i64_i32 v[98:99], s[48:49], v104, s66, v[98:99]
	v_lshl_add_u64 v[98:99], s[42:43], 1, v[98:99]
	v_lshlrev_b32_e32 v180, 1, v186
	v_lshl_add_u64 v[98:99], v[98:99], 0, v[180:181]
	global_store_dwordx4 v[98:99], v[100:103], off nt
	v_add_co_u32_e32 v98, vcc, 0x2000, v98
	s_nop 1
	v_addc_co_u32_e32 v99, vcc, 0, v99, vcc
	global_store_dwordx4 v[98:99], v[110:113], off offset:3072 nt
	s_branch .LBB0_1215
.LBB0_1218:
	v_and_b32_e32 v103, 0xfc, v199
	s_add_i32 s8, s42, 0x1580
	v_add_u32_e32 v98, s8, v103
	v_or_b32_e32 v101, s42, v103
	v_cmp_gt_u32_e32 vcc, s64, v103
	v_ashrrev_i32_e32 v99, 6, v198
	v_mul_lo_u32 v100, v99, s65
	v_cndmask_b32_e32 v98, v98, v101, vcc
	v_lshl_add_u32 v101, s10, 2, v99
	v_cmp_gt_i32_e64 s[8:9], s64, v198
	v_lshl_add_u32 v102, v103, 2, 0
	v_ashrrev_i32_e32 v99, 31, v98
	s_and_saveexec_b64 s[10:11], s[8:9]
	s_cbranch_execz .LBB0_1220
	v_add_u32_e32 v104, v102, v100
	s_waitcnt lgkmcnt(2)
	ds_read_b128 v[104:107], v104 offset:2080
	s_waitcnt lgkmcnt(2)
	v_mov_b64_e32 v[108:109], s[14:15]
	v_mad_i64_i32 v[108:109], s[44:45], v101, s67, v[108:109]
	v_lshl_add_u64 v[108:109], v[98:99], 2, v[108:109]
	s_waitcnt lgkmcnt(0)
	global_store_dwordx4 v[108:109], v[104:107], off nt

.LBB0_1223:
	v_or_b32_e32 v1, s46, v193
	v_mad_u64_u32 v[46:47], s[48:49], v1, s65, v[96:97]
	ds_read_b128 v[2:5], v46
	ds_read_b128 v[6:9], v46 offset:512
	ds_read_b128 v[10:13], v46 offset:1040
	ds_read_b128 v[14:17], v46 offset:1552
	ds_read_b128 v[18:21], v46 offset:2080
	ds_read_b128 v[22:25], v46 offset:2592
	ds_read_b128 v[26:29], v46 offset:3120
	ds_read_b128 v[30:33], v46 offset:3632
	ds_read_b128 v[34:37], v46 offset:4160
	ds_read_b128 v[38:41], v46 offset:4672
	ds_read_b128 v[42:45], v46 offset:5200
	ds_read_b128 v[46:49], v46 offset:5712
	s_waitcnt lgkmcnt(11)
	v_pk_fma_f32 v[4:5], v[66:67], v[4:5], v[78:79]
	v_pk_fma_f32 v[2:3], v[64:65], v[2:3], v[76:77]
	s_waitcnt lgkmcnt(10)
	v_pk_fma_f32 v[6:7], v[80:81], v[6:7], v[92:93]
	s_waitcnt lgkmcnt(9)
	v_pk_fma_f32 v[54:55], v[64:65], v[10:11], v[76:77]
	s_waitcnt lgkmcnt(8)
	v_pk_fma_f32 v[56:57], v[80:81], v[14:15], v[92:93]
	v_pk_fma_f32 v[58:59], v[66:67], v[12:13], v[78:79]
	s_waitcnt lgkmcnt(7)
	v_pk_fma_f32 v[62:63], v[64:65], v[18:19], v[76:77]
	v_pk_fma_f32 v[106:107], v[66:67], v[20:21], v[78:79]
	s_waitcnt lgkmcnt(5)
	v_pk_fma_f32 v[110:111], v[64:65], v[26:27], v[76:77]
	v_pk_fma_f32 v[114:115], v[66:67], v[28:29], v[78:79]
	v_pk_fma_f32 v[8:9], v[82:83], v[8:9], v[94:95]
	v_pk_fma_f32 v[60:61], v[82:83], v[16:17], v[94:95]
	v_pk_fma_f32 v[104:105], v[80:81], v[22:23], v[92:93]
	v_pk_fma_f32 v[108:109], v[82:83], v[24:25], v[94:95]
	s_waitcnt lgkmcnt(4)
	v_pk_fma_f32 v[112:113], v[80:81], v[30:31], v[92:93]
	v_pk_fma_f32 v[116:117], v[82:83], v[32:33], v[94:95]
	v_pk_fma_f32 v[2:3], v[68:69], v[10:11], v[2:3]
	v_pk_fma_f32 v[6:7], v[84:85], v[14:15], v[6:7]
	v_pk_fma_f32 v[4:5], v[70:71], v[12:13], v[4:5]
	v_pk_fma_f32 v[10:11], v[68:69], v[18:19], v[54:55]
	v_pk_fma_f32 v[12:13], v[84:85], v[22:23], v[56:57]
	v_pk_fma_f32 v[14:15], v[70:71], v[20:21], v[58:59]
	v_pk_fma_f32 v[54:55], v[68:69], v[26:27], v[62:63]
	v_pk_fma_f32 v[58:59], v[70:71], v[28:29], v[106:107]
	s_waitcnt lgkmcnt(3)
	v_pk_fma_f32 v[62:63], v[68:69], v[34:35], v[110:111]
	v_pk_fma_f32 v[106:107], v[70:71], v[36:37], v[114:115]
	v_mov_b64_e32 v[50:51], s[80:81]
	v_add_u32_e32 v1, v0, v1
	v_pk_fma_f32 v[8:9], v[86:87], v[16:17], v[8:9]
	v_pk_fma_f32 v[16:17], v[86:87], v[24:25], v[60:61]
	v_pk_fma_f32 v[56:57], v[84:85], v[30:31], v[104:105]
	v_pk_fma_f32 v[60:61], v[86:87], v[32:33], v[108:109]
	s_waitcnt lgkmcnt(2)
	v_pk_fma_f32 v[104:105], v[84:85], v[38:39], v[112:113]
	v_pk_fma_f32 v[108:109], v[86:87], v[40:41], v[116:117]
	v_pk_fma_f32 v[2:3], v[72:73], v[18:19], v[2:3]
	v_pk_fma_f32 v[6:7], v[88:89], v[22:23], v[6:7]
	v_pk_fma_f32 v[4:5], v[74:75], v[20:21], v[4:5]
	v_pk_fma_f32 v[10:11], v[72:73], v[26:27], v[10:11]
	v_pk_fma_f32 v[12:13], v[88:89], v[30:31], v[12:13]
	v_pk_fma_f32 v[14:15], v[74:75], v[28:29], v[14:15]
	v_pk_fma_f32 v[18:19], v[72:73], v[34:35], v[54:55]
	v_pk_fma_f32 v[22:23], v[74:75], v[36:37], v[58:59]
	s_waitcnt lgkmcnt(1)
	v_pk_fma_f32 v[26:27], v[72:73], v[42:43], v[62:63]
	v_pk_fma_f32 v[30:31], v[74:75], v[44:45], v[106:107]
	v_mad_i64_i32 v[50:51], s[48:49], v1, s66, v[50:51]
	v_pk_fma_f32 v[8:9], v[90:91], v[24:25], v[8:9]
	v_pk_fma_f32 v[16:17], v[90:91], v[32:33], v[16:17]
	v_pk_fma_f32 v[20:21], v[88:89], v[38:39], v[56:57]
	v_pk_fma_f32 v[24:25], v[90:91], v[40:41], v[60:61]
	s_waitcnt lgkmcnt(0)
	v_pk_fma_f32 v[28:29], v[88:89], v[46:47], v[104:105]
	v_pk_fma_f32 v[32:33], v[90:91], v[48:49], v[108:109]
	v_mul_f32_e32 v1, 0xbfb8aa3b, v2
	v_mul_f32_e32 v34, 0xbfb8aa3b, v3
	v_mul_f32_e32 v35, 0xbfb8aa3b, v4
	v_mul_f32_e32 v36, 0xbfb8aa3b, v5
	v_mul_f32_e32 v37, 0xbfb8aa3b, v10
	v_mul_f32_e32 v38, 0xbfb8aa3b, v11
	v_mul_f32_e32 v39, 0xbfb8aa3b, v14
	v_mul_f32_e32 v40, 0xbfb8aa3b, v15
	v_mul_f32_e32 v41, 0xbfb8aa3b, v18
	v_mul_f32_e32 v42, 0xbfb8aa3b, v19
	v_mul_f32_e32 v43, 0xbfb8aa3b, v22
	v_mul_f32_e32 v44, 0xbfb8aa3b, v23
	v_mul_f32_e32 v45, 0xbfb8aa3b, v26
	v_mul_f32_e32 v46, 0xbfb8aa3b, v27
	v_mul_f32_e32 v47, 0xbfb8aa3b, v30
	v_mul_f32_e32 v48, 0xbfb8aa3b, v31
	v_exp_f32_e32 v1, v1
	v_exp_f32_e32 v34, v34
	v_exp_f32_e32 v35, v35
	v_exp_f32_e32 v36, v36
	v_exp_f32_e32 v37, v37
	v_exp_f32_e32 v38, v38
	v_exp_f32_e32 v39, v39
	v_exp_f32_e32 v40, v40
	v_exp_f32_e32 v41, v41
	v_exp_f32_e32 v42, v42
	v_exp_f32_e32 v43, v43
	v_exp_f32_e32 v44, v44
	v_exp_f32_e32 v45, v45
	v_exp_f32_e32 v46, v46
	v_exp_f32_e32 v47, v47
	v_exp_f32_e32 v48, v48
	v_add_f32_e32 v1, 1.0, v1
	v_add_f32_e32 v49, 1.0, v34
	v_add_f32_e32 v54, 1.0, v35
	v_add_f32_e32 v55, 1.0, v36
	v_add_f32_e32 v56, 1.0, v37
	v_add_f32_e32 v57, 1.0, v38
	v_add_f32_e32 v58, 1.0, v39
	v_add_f32_e32 v59, 1.0, v40
	v_add_f32_e32 v60, 1.0, v41
	v_add_f32_e32 v61, 1.0, v42
	v_add_f32_e32 v62, 1.0, v43
	v_add_f32_e32 v63, 1.0, v44
	v_add_f32_e32 v103, 1.0, v45
	v_add_f32_e32 v104, 1.0, v46
	v_add_f32_e32 v105, 1.0, v47
	v_add_f32_e32 v106, 1.0, v48
	v_rcp_f32_e32 v34, v1
	v_rcp_f32_e32 v35, v49
	v_rcp_f32_e32 v36, v54
	v_rcp_f32_e32 v37, v55
	v_rcp_f32_e32 v38, v56
	v_rcp_f32_e32 v39, v57
	v_rcp_f32_e32 v40, v58
	v_rcp_f32_e32 v41, v59
	v_rcp_f32_e32 v42, v60
	v_rcp_f32_e32 v43, v61
	v_rcp_f32_e32 v44, v62
	v_rcp_f32_e32 v45, v63
	v_rcp_f32_e32 v46, v103
	v_rcp_f32_e32 v47, v104
	v_rcp_f32_e32 v48, v105
	v_rcp_f32_e32 v49, v106
	v_pk_mul_f32 v[2:3], v[2:3], v[34:35]
	v_pk_mul_f32 v[4:5], v[4:5], v[36:37]
	v_pk_mul_f32 v[10:11], v[10:11], v[38:39]
	v_pk_mul_f32 v[14:15], v[14:15], v[40:41]
	v_pk_mul_f32 v[18:19], v[18:19], v[42:43]
	v_pk_mul_f32 v[22:23], v[22:23], v[44:45]
	v_pk_mul_f32 v[26:27], v[26:27], v[46:47]
	v_pk_mul_f32 v[30:31], v[30:31], v[48:49]
	v_pk_mul_f32 v[2:3], v[6:7], v[2:3]
	v_pk_mul_f32 v[4:5], v[8:9], v[4:5]
	v_pk_mul_f32 v[6:7], v[12:13], v[10:11]
	v_pk_mul_f32 v[8:9], v[16:17], v[14:15]
	v_pk_mul_f32 v[10:11], v[20:21], v[18:19]
	v_pk_mul_f32 v[12:13], v[24:25], v[22:23]
	v_pk_mul_f32 v[14:15], v[28:29], v[26:27]
	v_pk_mul_f32 v[16:17], v[32:33], v[30:31]
	v_cvt_pk_bf16_f32 v1, v2, v3
	v_cvt_pk_bf16_f32 v2, v4, v5
	v_cvt_pk_bf16_f32 v3, v6, v7
	v_cvt_pk_bf16_f32 v4, v8, v9
	v_cvt_pk_bf16_f32 v5, v10, v11
	v_cvt_pk_bf16_f32 v6, v12, v13
	v_cvt_pk_bf16_f32 v7, v14, v15
	v_cvt_pk_bf16_f32 v8, v16, v17
	v_cndmask_b32_e64 v9, v2, v6, s[6:7]
	v_cndmask_b32_e64 v10, v1, v5, s[6:7]
	v_cndmask_b32_e64 v11, v4, v8, s[6:7]
	v_cndmask_b32_e64 v12, v3, v7, s[6:7]
	v_cndmask_b32_e64 v4, v8, v4, s[6:7]
	v_cndmask_b32_e64 v6, v6, v2, s[6:7]
	ds_bpermute_b32 v2, v97, v11
	ds_bpermute_b32 v8, v97, v12
	ds_bpermute_b32 v10, v97, v10
	ds_bpermute_b32 v11, v97, v9
	v_lshl_add_u64 v[50:51], s[42:43], 1, v[50:51]
	v_lshl_add_u64 v[50:51], v[50:51], 0, v[180:181]
	v_add_co_u32_e32 v52, vcc, 0x2000, v50
	s_and_b64 s[10:11], exec, s[44:45]
	s_nop 0
	v_addc_co_u32_e32 v53, vcc, 0, v51, vcc
	v_cndmask_b32_e64 v7, v7, v3, s[6:7]
	v_cndmask_b32_e64 v1, v5, v1, s[6:7]
	s_mov_b32 s46, 4
	s_mov_b64 s[44:45], 0
	s_waitcnt lgkmcnt(3)
	v_cndmask_b32_e64 v5, v4, v2, s[6:7]
	v_cndmask_b32_e64 v3, v2, v4, s[6:7]
	s_waitcnt lgkmcnt(2)
	v_cndmask_b32_e64 v4, v7, v8, s[6:7]
	v_cndmask_b32_e64 v2, v8, v7, s[6:7]
	s_waitcnt lgkmcnt(0)
	v_cndmask_b32_e64 v9, v6, v11, s[6:7]
	v_cndmask_b32_e64 v7, v11, v6, s[6:7]
	v_cndmask_b32_e64 v8, v1, v10, s[6:7]
	v_cndmask_b32_e64 v6, v10, v1, s[6:7]
	s_mov_b64 vcc, s[10:11]
	global_store_dwordx4 v[50:51], v[6:9], off nt
	global_store_dwordx4 v[52:53], v[2:5], off offset:3072 nt
	s_cbranch_vccnz .LBB0_1223
	s_and_saveexec_b64 s[6:7], s[8:9]
	s_cbranch_execz .LBB0_1205
	v_add3_u32 v0, v102, v100, s68
	ds_read_b128 v[0:3], v0
	v_add_u32_e32 v6, 2, v101
	v_mov_b64_e32 v[4:5], s[14:15]
	v_mad_i64_i32 v[4:5], s[8:9], v6, s67, v[4:5]
	v_lshl_add_u64 v[4:5], v[98:99], 2, v[4:5]
	s_waitcnt lgkmcnt(0)
	global_store_dwordx4 v[4:5], v[0:3], off nt
	s_branch .LBB0_1205

.LBB0_1332:
	v_mov_b32_e32 v130, v192
	s_lshl_b32 s28, s53, 8
	v_lshrrev_b32_e32 v128, 1, v130
	v_and_or_b32 v128, v128, 24, s28
	s_lshl_b32 s28, s52, 8
	s_add_i32 s28, s28, s45
	v_and_or_b32 v156, v130, 15, s28
	v_or_b32_e32 v128, s46, v128
	v_ashrrev_i32_e32 v157, 31, v156
	v_ashrrev_i32_e32 v129, 31, v128
	v_lshlrev_b64 v[130:131], 13, v[156:157]
	v_or_b32_e32 v178, 16, v156
	v_lshlrev_b64 v[154:155], 2, v[128:129]
	v_lshl_add_u64 v[130:131], s[76:77], 0, v[130:131]
	v_ashrrev_i32_e32 v179, 31, v178
	v_lshl_add_u64 v[128:129], s[22:23], 0, v[154:155]
	v_lshl_add_u64 v[190:191], v[130:131], 0, v[154:155]
	v_lshlrev_b64 v[178:179], 13, v[178:179]
	global_load_dwordx4 v[162:165], v[190:191], off nt
	global_load_dwordx4 v[140:143], v[128:129], off
	global_load_dwordx4 v[136:139], v[128:129], off offset:16
	global_load_dwordx4 v[166:169], v[190:191], off offset:16 nt
	global_load_dwordx4 v[170:173], v[190:191], off offset:512 nt
	global_load_dwordx4 v[132:135], v[128:129], off offset:512
	s_nop 0
	global_load_dwordx4 v[128:131], v[128:129], off offset:528
	s_nop 0
	global_load_dwordx4 v[174:177], v[190:191], off offset:528 nt
	v_lshl_add_u64 v[178:179], s[76:77], 0, v[178:179]
	v_lshl_add_u64 v[198:199], v[178:179], 0, v[154:155]
	global_load_dwordx4 v[178:181], v[198:199], off offset:528 nt
	global_load_dwordx4 v[182:185], v[198:199], off offset:512 nt
	global_load_dwordx4 v[186:189], v[198:199], off offset:16 nt
	global_load_dwordx4 v[194:197], v[198:199], off nt
	s_waitcnt vmcnt(0)
	v_pk_fma_f32 v[126:127], v[126:127], v[142:143], v[164:165]
	v_pk_fma_f32 v[124:125], v[124:125], v[140:141], v[162:163]
	v_pk_fma_f32 v[122:123], v[122:123], v[138:139], v[168:169]
	v_pk_fma_f32 v[120:121], v[120:121], v[136:137], v[166:167]
	v_pk_fma_f32 v[118:119], v[118:119], v[134:135], v[172:173]
	v_pk_fma_f32 v[116:117], v[116:117], v[132:133], v[170:171]
	v_pk_fma_f32 v[110:111], v[110:111], v[130:131], v[176:177]
	v_pk_fma_f32 v[108:109], v[108:109], v[128:129], v[174:175]
	global_store_dwordx4 v[190:191], v[124:127], off
	global_store_dwordx4 v[190:191], v[120:123], off offset:16
	global_store_dwordx4 v[190:191], v[116:119], off offset:512
	global_store_dwordx4 v[190:191], v[108:111], off offset:528
	s_nop 1
	v_or_b32_e32 v108, 32, v156
	v_ashrrev_i32_e32 v109, 31, v108
	v_lshlrev_b64 v[108:109], 13, v[108:109]
	v_lshl_add_u64 v[108:109], s[76:77], 0, v[108:109]
	v_lshl_add_u64 v[162:163], v[108:109], 0, v[154:155]
	global_load_dwordx4 v[108:111], v[162:163], off offset:528 nt
	global_load_dwordx4 v[116:119], v[162:163], off offset:512 nt
	global_load_dwordx4 v[120:123], v[162:163], off offset:16 nt
	global_load_dwordx4 v[124:127], v[162:163], off nt
	v_pk_fma_f32 v[114:115], v[114:115], v[142:143], v[196:197]
	v_pk_fma_f32 v[112:113], v[112:113], v[140:141], v[194:195]
	v_pk_fma_f32 v[106:107], v[106:107], v[138:139], v[188:189]
	v_pk_fma_f32 v[104:105], v[104:105], v[136:137], v[186:187]
	v_pk_fma_f32 v[102:103], v[102:103], v[134:135], v[184:185]
	v_pk_fma_f32 v[100:101], v[100:101], v[132:133], v[182:183]
	v_pk_fma_f32 v[94:95], v[94:95], v[130:131], v[180:181]
	v_pk_fma_f32 v[92:93], v[92:93], v[128:129], v[178:179]
	global_store_dwordx4 v[198:199], v[112:115], off
	global_store_dwordx4 v[198:199], v[104:107], off offset:16
	global_store_dwordx4 v[198:199], v[100:103], off offset:512
	global_store_dwordx4 v[198:199], v[92:95], off offset:528
	s_nop 1
	v_or_b32_e32 v92, 48, v156
	v_ashrrev_i32_e32 v93, 31, v92
	v_lshlrev_b64 v[92:93], 13, v[92:93]
	v_lshl_add_u64 v[92:93], s[76:77], 0, v[92:93]
	v_lshl_add_u64 v[164:165], v[92:93], 0, v[154:155]
	global_load_dwordx4 v[92:95], v[164:165], off offset:528 nt
	global_load_dwordx4 v[100:103], v[164:165], off offset:512 nt
	global_load_dwordx4 v[104:107], v[164:165], off offset:16 nt
	global_load_dwordx4 v[112:115], v[164:165], off nt
	s_waitcnt vmcnt(8)
	v_pk_fma_f32 v[98:99], v[98:99], v[142:143], v[126:127]
	v_pk_fma_f32 v[96:97], v[96:97], v[140:141], v[124:125]
	v_pk_fma_f32 v[90:91], v[90:91], v[138:139], v[122:123]
	v_pk_fma_f32 v[88:89], v[88:89], v[136:137], v[120:121]
	v_pk_fma_f32 v[86:87], v[86:87], v[134:135], v[118:119]
	v_pk_fma_f32 v[84:85], v[84:85], v[132:133], v[116:117]
	v_pk_fma_f32 v[78:79], v[78:79], v[130:131], v[110:111]
	v_pk_fma_f32 v[76:77], v[76:77], v[128:129], v[108:109]
	global_store_dwordx4 v[162:163], v[96:99], off
	global_store_dwordx4 v[162:163], v[88:91], off offset:16
	global_store_dwordx4 v[162:163], v[84:87], off offset:512
	global_store_dwordx4 v[162:163], v[76:79], off offset:528
	v_lshl_add_u64 v[108:109], v[190:191], 0, s[24:25]
	v_add_co_u32_e32 v110, vcc, s49, v190
	s_waitcnt vmcnt(4)
	v_pk_fma_f32 v[82:83], v[82:83], v[142:143], v[114:115]
	v_addc_co_u32_e32 v111, vcc, 0, v191, vcc
	global_load_dwordx4 v[76:79], v[108:109], off offset:528 nt
	global_load_dwordx4 v[84:87], v[110:111], off nt
	global_load_dwordx4 v[88:91], v[108:109], off offset:512 nt
	global_load_dwordx4 v[96:99], v[108:109], off offset:16 nt
	v_pk_fma_f32 v[80:81], v[80:81], v[140:141], v[112:113]
	v_pk_fma_f32 v[74:75], v[74:75], v[138:139], v[106:107]
	v_pk_fma_f32 v[72:73], v[72:73], v[136:137], v[104:105]
	v_pk_fma_f32 v[70:71], v[70:71], v[134:135], v[102:103]
	v_pk_fma_f32 v[68:69], v[68:69], v[132:133], v[100:101]
	v_pk_fma_f32 v[66:67], v[66:67], v[130:131], v[94:95]
	v_pk_fma_f32 v[64:65], v[64:65], v[128:129], v[92:93]
	global_store_dwordx4 v[164:165], v[80:83], off
	global_store_dwordx4 v[164:165], v[72:75], off offset:16
	global_store_dwordx4 v[164:165], v[68:71], off offset:512
	global_store_dwordx4 v[164:165], v[64:67], off offset:528
	s_nop 1
	v_add_u32_e32 v64, 0x90, v156
	v_ashrrev_i32_e32 v65, 31, v64
	v_lshlrev_b64 v[64:65], 13, v[64:65]
	v_lshl_add_u64 v[64:65], s[76:77], 0, v[64:65]
	v_lshl_add_u64 v[92:93], v[64:65], 0, v[154:155]
	global_load_dwordx4 v[64:67], v[92:93], off offset:528 nt
	global_load_dwordx4 v[68:71], v[92:93], off offset:512 nt
	global_load_dwordx4 v[72:75], v[92:93], off offset:16 nt
	global_load_dwordx4 v[80:83], v[92:93], off nt
	s_waitcnt vmcnt(10)
	v_pk_fma_f32 v[62:63], v[62:63], v[142:143], v[86:87]
	v_pk_fma_f32 v[60:61], v[60:61], v[140:141], v[84:85]
	s_waitcnt vmcnt(8)
	v_pk_fma_f32 v[58:59], v[58:59], v[138:139], v[98:99]
	v_pk_fma_f32 v[56:57], v[56:57], v[136:137], v[96:97]
	v_pk_fma_f32 v[54:55], v[54:55], v[134:135], v[90:91]
	v_pk_fma_f32 v[52:53], v[52:53], v[132:133], v[88:89]
	v_pk_fma_f32 v[46:47], v[46:47], v[130:131], v[78:79]
	v_pk_fma_f32 v[44:45], v[44:45], v[128:129], v[76:77]
	global_store_dwordx4 v[110:111], v[60:63], off
	global_store_dwordx4 v[108:109], v[56:59], off offset:16
	global_store_dwordx4 v[108:109], v[52:55], off offset:512
	global_store_dwordx4 v[108:109], v[44:47], off offset:528
	s_nop 1
	v_add_u32_e32 v44, 0xa0, v156
	v_ashrrev_i32_e32 v45, 31, v44
	v_lshlrev_b64 v[44:45], 13, v[44:45]
	v_lshl_add_u64 v[44:45], s[76:77], 0, v[44:45]
	v_lshl_add_u64 v[76:77], v[44:45], 0, v[154:155]
	global_load_dwordx4 v[44:47], v[76:77], off offset:528 nt
	global_load_dwordx4 v[52:55], v[76:77], off offset:512 nt
	global_load_dwordx4 v[56:59], v[76:77], off offset:16 nt
	global_load_dwordx4 v[60:63], v[76:77], off nt
	s_waitcnt vmcnt(8)
	v_pk_fma_f32 v[50:51], v[50:51], v[142:143], v[82:83]
	v_pk_fma_f32 v[48:49], v[48:49], v[140:141], v[80:81]
	v_pk_fma_f32 v[42:43], v[42:43], v[138:139], v[74:75]
	v_pk_fma_f32 v[40:41], v[40:41], v[136:137], v[72:73]
	v_pk_fma_f32 v[38:39], v[38:39], v[134:135], v[70:71]
	v_pk_fma_f32 v[36:37], v[36:37], v[132:133], v[68:69]
	v_pk_fma_f32 v[30:31], v[30:31], v[130:131], v[66:67]
	v_pk_fma_f32 v[28:29], v[28:29], v[128:129], v[64:65]
	global_store_dwordx4 v[92:93], v[48:51], off
	global_store_dwordx4 v[92:93], v[40:43], off offset:16
	global_store_dwordx4 v[92:93], v[36:39], off offset:512
	global_store_dwordx4 v[92:93], v[28:31], off offset:528
	s_nop 1
	v_add_u32_e32 v28, 0xb0, v156
	v_ashrrev_i32_e32 v29, 31, v28
	v_lshlrev_b64 v[28:29], 13, v[28:29]
	v_lshl_add_u64 v[28:29], s[76:77], 0, v[28:29]
	v_lshl_add_u64 v[64:65], v[28:29], 0, v[154:155]
	global_load_dwordx4 v[28:31], v[64:65], off offset:16 nt
	global_load_dwordx4 v[36:39], v[64:65], off nt
	global_load_dwordx4 v[40:43], v[64:65], off offset:528 nt
	global_load_dwordx4 v[48:51], v[64:65], off offset:512 nt
	s_waitcnt vmcnt(8)
	v_pk_fma_f32 v[34:35], v[34:35], v[142:143], v[62:63]
	v_pk_fma_f32 v[32:33], v[32:33], v[140:141], v[60:61]
	v_pk_fma_f32 v[26:27], v[26:27], v[138:139], v[58:59]
	v_pk_fma_f32 v[24:25], v[24:25], v[136:137], v[56:57]
	v_pk_fma_f32 v[18:19], v[18:19], v[134:135], v[54:55]
	v_pk_fma_f32 v[16:17], v[16:17], v[132:133], v[52:53]
	v_pk_fma_f32 v[10:11], v[10:11], v[130:131], v[46:47]
	v_pk_fma_f32 v[8:9], v[8:9], v[128:129], v[44:45]
	global_store_dwordx4 v[76:77], v[32:35], off
	global_store_dwordx4 v[76:77], v[24:27], off offset:16
	global_store_dwordx4 v[76:77], v[16:19], off offset:512
	global_store_dwordx4 v[76:77], v[8:11], off offset:528
	s_waitcnt vmcnt(6)
	s_nop 0
	v_pk_fma_f32 v[10:11], v[22:23], v[142:143], v[38:39]
	v_pk_fma_f32 v[8:9], v[20:21], v[140:141], v[36:37]
	global_store_dwordx4 v[64:65], v[8:11], off
	s_waitcnt vmcnt(5)
	v_pk_fma_f32 v[6:7], v[6:7], v[134:135], v[50:51]
	v_pk_fma_f32 v[4:5], v[4:5], v[132:133], v[48:49]
	v_pk_fma_f32 v[10:11], v[14:15], v[138:139], v[30:31]
	v_pk_fma_f32 v[8:9], v[12:13], v[136:137], v[28:29]
	v_pk_fma_f32 v[2:3], v[2:3], v[130:131], v[42:43]
	v_pk_fma_f32 v[0:1], v[0:1], v[128:129], v[40:41]
	global_store_dwordx4 v[64:65], v[8:11], off offset:16
	global_store_dwordx4 v[64:65], v[4:7], off offset:512
	global_store_dwordx4 v[64:65], v[0:3], off offset:528
	s_and_b64 vcc, exec, s[0:1]
	s_mov_b64 s[0:1], -1
	s_cbranch_vccnz .LBB0_1317
	s_andn2_b64 vcc, exec, s[10:11]
	s_cbranch_vccnz .LBB0_1316
	s_barrier
	s_branch .LBB0_1316
